# GEMM K-loops: s_setprio 0 moved behind the end-of-block barrier so the MFMA half (last arriver) reaches the barrier one issue slot earlier
# speedup vs baseline: 1.0107x; 1.0107x over previous
.LBB0_168:
	s_add_u32 s46, s66, 0xfff80080
	s_addc_u32 s47, s67, -1
	s_add_i32 s62, 0, 0x10000
	s_cmp_eq_u32 s82, 28
	s_cselect_b32 s69, s17, s47
	s_cselect_b32 s68, s65, s46
	v_add_u32_e32 v143, s62, v140
	s_cselect_b32 s61, s13, s81
	s_cselect_b32 s60, s79, s80
	s_add_i32 s63, 0, 0x14000
	ds_read_b128 v[144:147], v143
	ds_read_b128 v[148:151], v143 offset:1024
	ds_read_b128 v[152:155], v143 offset:2048
	ds_read_b128 v[156:159], v143 offset:3072
	v_add_u32_e32 v143, s63, v140
	ds_read_b128 v[160:163], v143
	ds_read_b128 v[178:181], v143 offset:1024
	ds_read_b128 v[182:185], v143 offset:2048
	ds_read_b128 v[186:189], v143 offset:3072
	v_lshl_add_u64 v[164:165], s[66:67], 0, v[136:137]
	s_add_i32 m0, s19, 0xc000
	ds_read_b128 v[206:209], v142
	ds_read_b128 v[210:213], v142 offset:1024
	ds_read_b128 v[214:217], v142 offset:2048
	ds_read_b128 v[218:221], v142 offset:3072
	ds_read_b128 v[222:225], v142 offset:4096
	ds_read_b128 v[226:229], v142 offset:5120
	ds_read_b128 v[230:233], v142 offset:6144
	ds_read_b128 v[234:237], v142 offset:7168
	global_load_lds_dwordx4 v[164:165], off
	v_lshl_add_u64 v[164:165], s[66:67], 0, v[138:139]
	s_add_i32 m0, s19, 0xe000
	s_nop 0
	global_load_lds_dwordx4 v[164:165], off
	s_waitcnt vmcnt(8)
	s_waitcnt lgkmcnt(0)
	s_setprio 1
	s_waitcnt lgkmcnt(0)
	v_mfma_f32_16x16x32_bf16 v[126:129], v[144:147], v[206:209], v[126:129]
	v_mfma_f32_16x16x32_bf16 v[122:125], v[152:155], v[206:209], v[122:125]
	v_mfma_f32_16x16x32_bf16 v[118:121], v[144:147], v[214:217], v[118:121]
	v_mfma_f32_16x16x32_bf16 v[114:117], v[152:155], v[214:217], v[114:117]
	s_barrier
	v_mfma_f32_16x16x32_bf16 v[102:105], v[144:147], v[222:225], v[102:105]
	v_mfma_f32_16x16x32_bf16 v[98:101], v[152:155], v[222:225], v[98:101]
	v_mfma_f32_16x16x32_bf16 v[86:89], v[144:147], v[230:233], v[86:89]
	v_mfma_f32_16x16x32_bf16 v[82:85], v[152:155], v[230:233], v[82:85]
	v_mfma_f32_16x16x32_bf16 v[126:129], v[148:151], v[210:213], v[126:129]
	v_mfma_f32_16x16x32_bf16 v[122:125], v[156:159], v[210:213], v[122:125]
	v_mfma_f32_16x16x32_bf16 v[118:121], v[148:151], v[218:221], v[118:121]
	v_mfma_f32_16x16x32_bf16 v[114:117], v[156:159], v[218:221], v[114:117]
	v_mfma_f32_16x16x32_bf16 v[102:105], v[148:151], v[226:229], v[102:105]
	v_mfma_f32_16x16x32_bf16 v[98:101], v[156:159], v[226:229], v[98:101]
	v_mfma_f32_16x16x32_bf16 v[86:89], v[148:151], v[234:237], v[86:89]
	v_mfma_f32_16x16x32_bf16 v[82:85], v[156:159], v[234:237], v[82:85]
	s_setprio 0
	s_setprio 1
	v_mfma_f32_16x16x32_bf16 v[110:113], v[160:163], v[206:209], v[110:113]
	v_mfma_f32_16x16x32_bf16 v[106:109], v[182:185], v[206:209], v[106:109]
	v_mfma_f32_16x16x32_bf16 v[94:97], v[160:163], v[214:217], v[94:97]
	v_mfma_f32_16x16x32_bf16 v[90:93], v[182:185], v[214:217], v[90:93]
	v_mfma_f32_16x16x32_bf16 v[78:81], v[160:163], v[222:225], v[78:81]
	v_mfma_f32_16x16x32_bf16 v[74:77], v[182:185], v[222:225], v[74:77]
	v_mfma_f32_16x16x32_bf16 v[70:73], v[160:163], v[230:233], v[70:73]
	v_mfma_f32_16x16x32_bf16 v[66:69], v[182:185], v[230:233], v[66:69]
	v_mfma_f32_16x16x32_bf16 v[110:113], v[178:181], v[210:213], v[110:113]
	v_mfma_f32_16x16x32_bf16 v[106:109], v[186:189], v[210:213], v[106:109]
	v_mfma_f32_16x16x32_bf16 v[94:97], v[178:181], v[218:221], v[94:97]
	v_mfma_f32_16x16x32_bf16 v[90:93], v[186:189], v[218:221], v[90:93]
	v_mfma_f32_16x16x32_bf16 v[78:81], v[178:181], v[226:229], v[78:81]
	v_mfma_f32_16x16x32_bf16 v[74:77], v[186:189], v[226:229], v[74:77]
	v_mfma_f32_16x16x32_bf16 v[70:73], v[178:181], v[234:237], v[70:73]
	v_mfma_f32_16x16x32_bf16 v[66:69], v[186:189], v[234:237], v[66:69]
	s_barrier
	s_setprio 0
	s_add_i32 s46, s62, s71
	v_lshl_add_u64 v[164:165], s[60:61], 0, v[166:167]
	s_mov_b32 m0, s46
	ds_read_b128 v[206:209], v142 offset:16384
	ds_read_b128 v[210:213], v142 offset:17408
	ds_read_b128 v[214:217], v142 offset:18432
	ds_read_b128 v[218:221], v142 offset:19456
	ds_read_b128 v[222:225], v142 offset:20480
	ds_read_b128 v[226:229], v142 offset:21504
	ds_read_b128 v[230:233], v142 offset:22528
	ds_read_b128 v[234:237], v142 offset:23552
	global_load_lds_dwordx4 v[164:165], off
	s_add_i32 m0, s46, 0x2000
	s_add_u32 s46, s60, 0x80000
	v_lshl_add_u64 v[242:243], s[60:61], 0, v[130:131]
	s_addc_u32 s47, s61, 0
	s_add_i32 s62, s63, s71
	global_load_lds_dwordx4 v[242:243], off
	v_lshl_add_u64 v[244:245], s[46:47], 0, v[166:167]
	s_mov_b32 m0, s62
	v_lshl_add_u64 v[246:247], s[68:69], 0, v[132:133]
	global_load_lds_dwordx4 v[244:245], off
	v_lshl_add_u64 v[244:245], s[46:47], 0, v[130:131]
	s_add_i32 m0, s62, 0x2000
	s_nop 0
	global_load_lds_dwordx4 v[244:245], off
	v_lshl_add_u64 v[244:245], s[68:69], 0, v[134:135]
	s_mov_b32 m0, s19
	s_nop 0
	global_load_lds_dwordx4 v[244:245], off
	s_mov_b32 m0, s73
	s_nop 0
	global_load_lds_dwordx4 v[246:247], off
	s_waitcnt vmcnt(8)
	s_waitcnt lgkmcnt(0)
	s_setprio 1
	s_waitcnt lgkmcnt(0)
	v_mfma_f32_16x16x32_bf16 v[62:65], v[144:147], v[206:209], v[62:65]
	v_mfma_f32_16x16x32_bf16 v[58:61], v[152:155], v[206:209], v[58:61]
	v_mfma_f32_16x16x32_bf16 v[54:57], v[144:147], v[214:217], v[54:57]
	v_mfma_f32_16x16x32_bf16 v[50:53], v[152:155], v[214:217], v[50:53]
	s_barrier
	v_mfma_f32_16x16x32_bf16 v[38:41], v[144:147], v[222:225], v[38:41]
	v_mfma_f32_16x16x32_bf16 v[34:37], v[152:155], v[222:225], v[34:37]
	v_mfma_f32_16x16x32_bf16 v[22:25], v[144:147], v[230:233], v[22:25]
	v_mfma_f32_16x16x32_bf16 v[18:21], v[152:155], v[230:233], v[18:21]
	v_mfma_f32_16x16x32_bf16 v[62:65], v[148:151], v[210:213], v[62:65]
	v_mfma_f32_16x16x32_bf16 v[58:61], v[156:159], v[210:213], v[58:61]
	v_mfma_f32_16x16x32_bf16 v[54:57], v[148:151], v[218:221], v[54:57]
	v_mfma_f32_16x16x32_bf16 v[50:53], v[156:159], v[218:221], v[50:53]
	v_mfma_f32_16x16x32_bf16 v[38:41], v[148:151], v[226:229], v[38:41]
	v_mfma_f32_16x16x32_bf16 v[34:37], v[156:159], v[226:229], v[34:37]
	v_mfma_f32_16x16x32_bf16 v[22:25], v[148:151], v[234:237], v[22:25]
	v_mfma_f32_16x16x32_bf16 v[18:21], v[156:159], v[234:237], v[18:21]
	s_setprio 0
	s_setprio 1
	v_mfma_f32_16x16x32_bf16 v[46:49], v[160:163], v[206:209], v[46:49]
	v_mfma_f32_16x16x32_bf16 v[42:45], v[182:185], v[206:209], v[42:45]
	v_mfma_f32_16x16x32_bf16 v[30:33], v[160:163], v[214:217], v[30:33]
	v_mfma_f32_16x16x32_bf16 v[26:29], v[182:185], v[214:217], v[26:29]
	v_mfma_f32_16x16x32_bf16 v[14:17], v[160:163], v[222:225], v[14:17]
	v_mfma_f32_16x16x32_bf16 v[10:13], v[182:185], v[222:225], v[10:13]
	v_mfma_f32_16x16x32_bf16 v[6:9], v[160:163], v[230:233], v[6:9]
	v_mfma_f32_16x16x32_bf16 v[2:5], v[182:185], v[230:233], v[2:5]
	v_mfma_f32_16x16x32_bf16 v[46:49], v[178:181], v[210:213], v[46:49]
	v_mfma_f32_16x16x32_bf16 v[42:45], v[186:189], v[210:213], v[42:45]
	v_mfma_f32_16x16x32_bf16 v[30:33], v[178:181], v[218:221], v[30:33]
	v_mfma_f32_16x16x32_bf16 v[26:29], v[186:189], v[218:221], v[26:29]
	v_mfma_f32_16x16x32_bf16 v[14:17], v[178:181], v[226:229], v[14:17]
	v_mfma_f32_16x16x32_bf16 v[10:13], v[186:189], v[226:229], v[10:13]
	v_mfma_f32_16x16x32_bf16 v[6:9], v[178:181], v[234:237], v[6:9]
	v_mfma_f32_16x16x32_bf16 v[2:5], v[186:189], v[234:237], v[2:5]
	s_barrier
	s_setprio 0
	s_add_i32 s62, 0, 0x18000
	v_add_u32_e32 v143, s62, v140
	s_add_i32 s63, 0, 0x1c000
	ds_read_b128 v[144:147], v143
	ds_read_b128 v[148:151], v143 offset:1024
	ds_read_b128 v[152:155], v143 offset:2048
	ds_read_b128 v[156:159], v143 offset:3072
	v_add_u32_e32 v143, s63, v140
	ds_read_b128 v[160:163], v143
	ds_read_b128 v[178:181], v143 offset:1024
	ds_read_b128 v[182:185], v143 offset:2048
	ds_read_b128 v[186:189], v143 offset:3072
	s_add_u32 s46, s68, 0x80000
	s_addc_u32 s47, s69, 0
	s_mov_b32 m0, s74
	v_lshl_add_u64 v[248:249], s[46:47], 0, v[134:135]
	ds_read_b128 v[206:209], v142 offset:32768
	ds_read_b128 v[210:213], v142 offset:33792
	ds_read_b128 v[214:217], v142 offset:34816
	ds_read_b128 v[218:221], v142 offset:35840
	ds_read_b128 v[222:225], v142 offset:36864
	ds_read_b128 v[226:229], v142 offset:37888
	ds_read_b128 v[230:233], v142 offset:38912
	ds_read_b128 v[234:237], v142 offset:39936
	global_load_lds_dwordx4 v[248:249], off
	v_lshl_add_u64 v[248:249], s[46:47], 0, v[132:133]
	s_mov_b32 m0, s75
	s_nop 0
	global_load_lds_dwordx4 v[248:249], off
	s_waitcnt vmcnt(8)
	s_waitcnt lgkmcnt(0)
	s_setprio 1
	s_waitcnt lgkmcnt(0)
	v_mfma_f32_16x16x32_bf16 v[126:129], v[144:147], v[206:209], v[126:129]
	v_mfma_f32_16x16x32_bf16 v[122:125], v[152:155], v[206:209], v[122:125]
	v_mfma_f32_16x16x32_bf16 v[118:121], v[144:147], v[214:217], v[118:121]
	v_mfma_f32_16x16x32_bf16 v[114:117], v[152:155], v[214:217], v[114:117]
	s_barrier
	v_mfma_f32_16x16x32_bf16 v[102:105], v[144:147], v[222:225], v[102:105]
	v_mfma_f32_16x16x32_bf16 v[98:101], v[152:155], v[222:225], v[98:101]
	v_mfma_f32_16x16x32_bf16 v[86:89], v[144:147], v[230:233], v[86:89]
	v_mfma_f32_16x16x32_bf16 v[82:85], v[152:155], v[230:233], v[82:85]
	v_mfma_f32_16x16x32_bf16 v[126:129], v[148:151], v[210:213], v[126:129]
	v_mfma_f32_16x16x32_bf16 v[122:125], v[156:159], v[210:213], v[122:125]
	v_mfma_f32_16x16x32_bf16 v[118:121], v[148:151], v[218:221], v[118:121]
	v_mfma_f32_16x16x32_bf16 v[114:117], v[156:159], v[218:221], v[114:117]
	v_mfma_f32_16x16x32_bf16 v[102:105], v[148:151], v[226:229], v[102:105]
	v_mfma_f32_16x16x32_bf16 v[98:101], v[156:159], v[226:229], v[98:101]
	v_mfma_f32_16x16x32_bf16 v[86:89], v[148:151], v[234:237], v[86:89]
	v_mfma_f32_16x16x32_bf16 v[82:85], v[156:159], v[234:237], v[82:85]
	s_setprio 0
	s_setprio 1
	v_mfma_f32_16x16x32_bf16 v[110:113], v[160:163], v[206:209], v[110:113]
	v_mfma_f32_16x16x32_bf16 v[106:109], v[182:185], v[206:209], v[106:109]
	v_mfma_f32_16x16x32_bf16 v[94:97], v[160:163], v[214:217], v[94:97]
	v_mfma_f32_16x16x32_bf16 v[90:93], v[182:185], v[214:217], v[90:93]
	v_mfma_f32_16x16x32_bf16 v[78:81], v[160:163], v[222:225], v[78:81]
	v_mfma_f32_16x16x32_bf16 v[74:77], v[182:185], v[222:225], v[74:77]
	v_mfma_f32_16x16x32_bf16 v[70:73], v[160:163], v[230:233], v[70:73]
	v_mfma_f32_16x16x32_bf16 v[66:69], v[182:185], v[230:233], v[66:69]
	v_mfma_f32_16x16x32_bf16 v[110:113], v[178:181], v[210:213], v[110:113]
	v_mfma_f32_16x16x32_bf16 v[106:109], v[186:189], v[210:213], v[106:109]
	v_mfma_f32_16x16x32_bf16 v[94:97], v[178:181], v[218:221], v[94:97]
	v_mfma_f32_16x16x32_bf16 v[90:93], v[186:189], v[218:221], v[90:93]
	v_mfma_f32_16x16x32_bf16 v[78:81], v[178:181], v[226:229], v[78:81]
	v_mfma_f32_16x16x32_bf16 v[74:77], v[186:189], v[226:229], v[74:77]
	v_mfma_f32_16x16x32_bf16 v[70:73], v[178:181], v[234:237], v[70:73]
	v_mfma_f32_16x16x32_bf16 v[66:69], v[186:189], v[234:237], v[66:69]
	s_barrier
	s_setprio 0
	s_add_i32 s46, s62, s71
	v_lshl_add_u64 v[164:165], v[164:165], 0, s[42:43]
	s_mov_b32 m0, s46
	ds_read_b128 v[206:209], v142 offset:49152
	ds_read_b128 v[210:213], v142 offset:50176
	ds_read_b128 v[214:217], v142 offset:51200
	ds_read_b128 v[218:221], v142 offset:52224
	ds_read_b128 v[222:225], v142 offset:53248
	ds_read_b128 v[226:229], v142 offset:54272
	ds_read_b128 v[230:233], v142 offset:55296
	ds_read_b128 v[234:237], v142 offset:56320
	global_load_lds_dwordx4 v[164:165], off
	s_add_i32 m0, s46, 0x2000
	s_add_u32 s46, s60, 0x80080
	v_lshl_add_u64 v[164:165], v[242:243], 0, s[42:43]
	s_addc_u32 s47, s61, 0
	s_add_i32 s60, s63, s71
	global_load_lds_dwordx4 v[164:165], off
	v_lshl_add_u64 v[164:165], s[46:47], 0, v[166:167]
	s_mov_b32 m0, s60
	s_nop 0
	global_load_lds_dwordx4 v[164:165], off
	v_lshl_add_u64 v[164:165], s[46:47], 0, v[130:131]
	s_add_i32 m0, s60, 0x2000
	s_nop 0
	global_load_lds_dwordx4 v[164:165], off
	v_lshl_add_u64 v[164:165], v[244:245], 0, s[42:43]
	s_mov_b32 m0, s76
	s_nop 0
	global_load_lds_dwordx4 v[164:165], off
	v_lshl_add_u64 v[164:165], v[246:247], 0, s[42:43]
	s_mov_b32 m0, s77
	s_nop 0
	global_load_lds_dwordx4 v[164:165], off
	s_waitcnt vmcnt(8)
	s_waitcnt lgkmcnt(0)
	s_setprio 1
	s_waitcnt lgkmcnt(0)
	v_mfma_f32_16x16x32_bf16 v[62:65], v[144:147], v[206:209], v[62:65]
	v_mfma_f32_16x16x32_bf16 v[58:61], v[152:155], v[206:209], v[58:61]
	v_mfma_f32_16x16x32_bf16 v[54:57], v[144:147], v[214:217], v[54:57]
	v_mfma_f32_16x16x32_bf16 v[50:53], v[152:155], v[214:217], v[50:53]
	s_barrier
	v_mfma_f32_16x16x32_bf16 v[38:41], v[144:147], v[222:225], v[38:41]
	v_mfma_f32_16x16x32_bf16 v[34:37], v[152:155], v[222:225], v[34:37]
	v_mfma_f32_16x16x32_bf16 v[22:25], v[144:147], v[230:233], v[22:25]
	v_mfma_f32_16x16x32_bf16 v[18:21], v[152:155], v[230:233], v[18:21]
	v_mfma_f32_16x16x32_bf16 v[62:65], v[148:151], v[210:213], v[62:65]
	v_mfma_f32_16x16x32_bf16 v[58:61], v[156:159], v[210:213], v[58:61]
	v_mfma_f32_16x16x32_bf16 v[54:57], v[148:151], v[218:221], v[54:57]
	v_mfma_f32_16x16x32_bf16 v[50:53], v[156:159], v[218:221], v[50:53]
	v_mfma_f32_16x16x32_bf16 v[38:41], v[148:151], v[226:229], v[38:41]
	v_mfma_f32_16x16x32_bf16 v[34:37], v[156:159], v[226:229], v[34:37]
	v_mfma_f32_16x16x32_bf16 v[22:25], v[148:151], v[234:237], v[22:25]
	v_mfma_f32_16x16x32_bf16 v[18:21], v[156:159], v[234:237], v[18:21]
	s_setprio 0
	s_setprio 1
	v_mfma_f32_16x16x32_bf16 v[46:49], v[160:163], v[206:209], v[46:49]
	v_mfma_f32_16x16x32_bf16 v[42:45], v[182:185], v[206:209], v[42:45]
	v_mfma_f32_16x16x32_bf16 v[30:33], v[160:163], v[214:217], v[30:33]
	v_mfma_f32_16x16x32_bf16 v[26:29], v[182:185], v[214:217], v[26:29]
	v_mfma_f32_16x16x32_bf16 v[14:17], v[160:163], v[222:225], v[14:17]
	v_mfma_f32_16x16x32_bf16 v[10:13], v[182:185], v[222:225], v[10:13]
	v_mfma_f32_16x16x32_bf16 v[6:9], v[160:163], v[230:233], v[6:9]
	v_mfma_f32_16x16x32_bf16 v[2:5], v[182:185], v[230:233], v[2:5]
	v_mfma_f32_16x16x32_bf16 v[46:49], v[178:181], v[210:213], v[46:49]
	v_mfma_f32_16x16x32_bf16 v[42:45], v[186:189], v[210:213], v[42:45]
	v_mfma_f32_16x16x32_bf16 v[30:33], v[178:181], v[218:221], v[30:33]
	v_mfma_f32_16x16x32_bf16 v[26:29], v[186:189], v[218:221], v[26:29]
	v_mfma_f32_16x16x32_bf16 v[14:17], v[178:181], v[226:229], v[14:17]
	v_mfma_f32_16x16x32_bf16 v[10:13], v[186:189], v[226:229], v[10:13]
	v_mfma_f32_16x16x32_bf16 v[6:9], v[178:181], v[234:237], v[6:9]
	v_mfma_f32_16x16x32_bf16 v[2:5], v[186:189], v[234:237], v[2:5]
	s_barrier
	s_setprio 0
	s_add_i32 s82, s82, 2
	s_add_u32 s66, s66, 0x100
	s_addc_u32 s67, s67, 0
	s_add_u32 s80, s80, 0x100
	s_addc_u32 s81, s81, 0
	s_cmp_gt_u32 s82, 29
	s_cbranch_scc0 .LBB0_168
	s_and_b64 vcc, exec, s[10:11]
	s_cbranch_vccz .LBB0_171
	s_barrier

.LBB0_426:
	s_add_u32 s46, s66, 0xfffe0080
	s_addc_u32 s47, s67, -1
	s_add_i32 s62, 0, 0x10000
	s_cmp_eq_u32 s84, 4
	s_cselect_b32 s69, s19, s47
	s_cselect_b32 s68, s80, s46
	v_add_u32_e32 v143, s62, v140
	s_cselect_b32 s61, s17, s83
	s_cselect_b32 s60, s81, s82
	s_add_i32 s63, 0, 0x14000
	ds_read_b128 v[144:147], v143
	ds_read_b128 v[148:151], v143 offset:1024
	ds_read_b128 v[152:155], v143 offset:2048
	ds_read_b128 v[156:159], v143 offset:3072
	v_add_u32_e32 v143, s63, v140
	ds_read_b128 v[160:163], v143
	ds_read_b128 v[178:181], v143 offset:1024
	ds_read_b128 v[182:185], v143 offset:2048
	ds_read_b128 v[186:189], v143 offset:3072
	v_lshl_add_u64 v[164:165], s[66:67], 0, v[136:137]
	s_add_i32 m0, s11, 0xc000
	ds_read_b128 v[206:209], v142
	ds_read_b128 v[210:213], v142 offset:1024
	ds_read_b128 v[214:217], v142 offset:2048
	ds_read_b128 v[218:221], v142 offset:3072
	ds_read_b128 v[222:225], v142 offset:4096
	ds_read_b128 v[226:229], v142 offset:5120
	ds_read_b128 v[230:233], v142 offset:6144
	ds_read_b128 v[234:237], v142 offset:7168
	global_load_lds_dwordx4 v[164:165], off
	v_lshl_add_u64 v[164:165], s[66:67], 0, v[138:139]
	s_add_i32 m0, s11, 0xe000
	s_nop 0
	global_load_lds_dwordx4 v[164:165], off
	s_waitcnt vmcnt(8)
	s_waitcnt lgkmcnt(0)
	s_setprio 1
	s_waitcnt lgkmcnt(0)
	v_mfma_f32_16x16x32_bf16 v[126:129], v[144:147], v[206:209], v[126:129]
	v_mfma_f32_16x16x32_bf16 v[122:125], v[152:155], v[206:209], v[122:125]
	v_mfma_f32_16x16x32_bf16 v[118:121], v[144:147], v[214:217], v[118:121]
	v_mfma_f32_16x16x32_bf16 v[114:117], v[152:155], v[214:217], v[114:117]
	s_barrier
	v_mfma_f32_16x16x32_bf16 v[102:105], v[144:147], v[222:225], v[102:105]
	v_mfma_f32_16x16x32_bf16 v[98:101], v[152:155], v[222:225], v[98:101]
	v_mfma_f32_16x16x32_bf16 v[86:89], v[144:147], v[230:233], v[86:89]
	v_mfma_f32_16x16x32_bf16 v[82:85], v[152:155], v[230:233], v[82:85]
	v_mfma_f32_16x16x32_bf16 v[126:129], v[148:151], v[210:213], v[126:129]
	v_mfma_f32_16x16x32_bf16 v[122:125], v[156:159], v[210:213], v[122:125]
	v_mfma_f32_16x16x32_bf16 v[118:121], v[148:151], v[218:221], v[118:121]
	v_mfma_f32_16x16x32_bf16 v[114:117], v[156:159], v[218:221], v[114:117]
	v_mfma_f32_16x16x32_bf16 v[102:105], v[148:151], v[226:229], v[102:105]
	v_mfma_f32_16x16x32_bf16 v[98:101], v[156:159], v[226:229], v[98:101]
	v_mfma_f32_16x16x32_bf16 v[86:89], v[148:151], v[234:237], v[86:89]
	v_mfma_f32_16x16x32_bf16 v[82:85], v[156:159], v[234:237], v[82:85]
	s_setprio 0
	s_setprio 1
	v_mfma_f32_16x16x32_bf16 v[110:113], v[160:163], v[206:209], v[110:113]
	v_mfma_f32_16x16x32_bf16 v[106:109], v[182:185], v[206:209], v[106:109]
	v_mfma_f32_16x16x32_bf16 v[94:97], v[160:163], v[214:217], v[94:97]
	v_mfma_f32_16x16x32_bf16 v[90:93], v[182:185], v[214:217], v[90:93]
	v_mfma_f32_16x16x32_bf16 v[78:81], v[160:163], v[222:225], v[78:81]
	v_mfma_f32_16x16x32_bf16 v[74:77], v[182:185], v[222:225], v[74:77]
	v_mfma_f32_16x16x32_bf16 v[70:73], v[160:163], v[230:233], v[70:73]
	v_mfma_f32_16x16x32_bf16 v[66:69], v[182:185], v[230:233], v[66:69]
	v_mfma_f32_16x16x32_bf16 v[110:113], v[178:181], v[210:213], v[110:113]
	v_mfma_f32_16x16x32_bf16 v[106:109], v[186:189], v[210:213], v[106:109]
	v_mfma_f32_16x16x32_bf16 v[94:97], v[178:181], v[218:221], v[94:97]
	v_mfma_f32_16x16x32_bf16 v[90:93], v[186:189], v[218:221], v[90:93]
	v_mfma_f32_16x16x32_bf16 v[78:81], v[178:181], v[226:229], v[78:81]
	v_mfma_f32_16x16x32_bf16 v[74:77], v[186:189], v[226:229], v[74:77]
	v_mfma_f32_16x16x32_bf16 v[70:73], v[178:181], v[234:237], v[70:73]
	v_mfma_f32_16x16x32_bf16 v[66:69], v[186:189], v[234:237], v[66:69]
	s_barrier
	s_setprio 0
	s_add_i32 s46, s62, s72
	v_lshl_add_u64 v[164:165], s[60:61], 0, v[166:167]
	s_mov_b32 m0, s46
	ds_read_b128 v[206:209], v142 offset:16384
	ds_read_b128 v[210:213], v142 offset:17408
	ds_read_b128 v[214:217], v142 offset:18432
	ds_read_b128 v[218:221], v142 offset:19456
	ds_read_b128 v[222:225], v142 offset:20480
	ds_read_b128 v[226:229], v142 offset:21504
	ds_read_b128 v[230:233], v142 offset:22528
	ds_read_b128 v[234:237], v142 offset:23552
	global_load_lds_dwordx4 v[164:165], off
	s_add_i32 m0, s46, 0x2000
	s_add_u32 s46, s60, 0x20000
	v_lshl_add_u64 v[242:243], s[60:61], 0, v[130:131]
	s_addc_u32 s47, s61, 0
	s_add_i32 s62, s63, s72
	global_load_lds_dwordx4 v[242:243], off
	v_lshl_add_u64 v[244:245], s[46:47], 0, v[166:167]
	s_mov_b32 m0, s62
	v_lshl_add_u64 v[246:247], s[68:69], 0, v[132:133]
	global_load_lds_dwordx4 v[244:245], off
	v_lshl_add_u64 v[244:245], s[46:47], 0, v[130:131]
	s_add_i32 m0, s62, 0x2000
	s_nop 0
	global_load_lds_dwordx4 v[244:245], off
	v_lshl_add_u64 v[244:245], s[68:69], 0, v[134:135]
	s_mov_b32 m0, s11
	s_nop 0
	global_load_lds_dwordx4 v[244:245], off
	s_mov_b32 m0, s74
	s_nop 0
	global_load_lds_dwordx4 v[246:247], off
	s_waitcnt vmcnt(8)
	s_waitcnt lgkmcnt(0)
	s_setprio 1
	s_waitcnt lgkmcnt(0)
	v_mfma_f32_16x16x32_bf16 v[62:65], v[144:147], v[206:209], v[62:65]
	v_mfma_f32_16x16x32_bf16 v[58:61], v[152:155], v[206:209], v[58:61]
	v_mfma_f32_16x16x32_bf16 v[54:57], v[144:147], v[214:217], v[54:57]
	v_mfma_f32_16x16x32_bf16 v[50:53], v[152:155], v[214:217], v[50:53]
	s_barrier
	v_mfma_f32_16x16x32_bf16 v[38:41], v[144:147], v[222:225], v[38:41]
	v_mfma_f32_16x16x32_bf16 v[34:37], v[152:155], v[222:225], v[34:37]
	v_mfma_f32_16x16x32_bf16 v[22:25], v[144:147], v[230:233], v[22:25]
	v_mfma_f32_16x16x32_bf16 v[18:21], v[152:155], v[230:233], v[18:21]
	v_mfma_f32_16x16x32_bf16 v[62:65], v[148:151], v[210:213], v[62:65]
	v_mfma_f32_16x16x32_bf16 v[58:61], v[156:159], v[210:213], v[58:61]
	v_mfma_f32_16x16x32_bf16 v[54:57], v[148:151], v[218:221], v[54:57]
	v_mfma_f32_16x16x32_bf16 v[50:53], v[156:159], v[218:221], v[50:53]
	v_mfma_f32_16x16x32_bf16 v[38:41], v[148:151], v[226:229], v[38:41]
	v_mfma_f32_16x16x32_bf16 v[34:37], v[156:159], v[226:229], v[34:37]
	v_mfma_f32_16x16x32_bf16 v[22:25], v[148:151], v[234:237], v[22:25]
	v_mfma_f32_16x16x32_bf16 v[18:21], v[156:159], v[234:237], v[18:21]
	s_setprio 0
	s_setprio 1
	v_mfma_f32_16x16x32_bf16 v[46:49], v[160:163], v[206:209], v[46:49]
	v_mfma_f32_16x16x32_bf16 v[42:45], v[182:185], v[206:209], v[42:45]
	v_mfma_f32_16x16x32_bf16 v[30:33], v[160:163], v[214:217], v[30:33]
	v_mfma_f32_16x16x32_bf16 v[26:29], v[182:185], v[214:217], v[26:29]
	v_mfma_f32_16x16x32_bf16 v[14:17], v[160:163], v[222:225], v[14:17]
	v_mfma_f32_16x16x32_bf16 v[10:13], v[182:185], v[222:225], v[10:13]
	v_mfma_f32_16x16x32_bf16 v[6:9], v[160:163], v[230:233], v[6:9]
	v_mfma_f32_16x16x32_bf16 v[2:5], v[182:185], v[230:233], v[2:5]
	v_mfma_f32_16x16x32_bf16 v[46:49], v[178:181], v[210:213], v[46:49]
	v_mfma_f32_16x16x32_bf16 v[42:45], v[186:189], v[210:213], v[42:45]
	v_mfma_f32_16x16x32_bf16 v[30:33], v[178:181], v[218:221], v[30:33]
	v_mfma_f32_16x16x32_bf16 v[26:29], v[186:189], v[218:221], v[26:29]
	v_mfma_f32_16x16x32_bf16 v[14:17], v[178:181], v[226:229], v[14:17]
	v_mfma_f32_16x16x32_bf16 v[10:13], v[186:189], v[226:229], v[10:13]
	v_mfma_f32_16x16x32_bf16 v[6:9], v[178:181], v[234:237], v[6:9]
	v_mfma_f32_16x16x32_bf16 v[2:5], v[186:189], v[234:237], v[2:5]
	s_barrier
	s_setprio 0
	s_add_i32 s62, 0, 0x18000
	v_add_u32_e32 v143, s62, v140
	s_add_i32 s63, 0, 0x1c000
	ds_read_b128 v[144:147], v143
	ds_read_b128 v[148:151], v143 offset:1024
	ds_read_b128 v[152:155], v143 offset:2048
	ds_read_b128 v[156:159], v143 offset:3072
	v_add_u32_e32 v143, s63, v140
	ds_read_b128 v[160:163], v143
	ds_read_b128 v[178:181], v143 offset:1024
	ds_read_b128 v[182:185], v143 offset:2048
	ds_read_b128 v[186:189], v143 offset:3072
	s_add_u32 s46, s68, 0x20000
	s_addc_u32 s47, s69, 0
	s_mov_b32 m0, s75
	v_lshl_add_u64 v[248:249], s[46:47], 0, v[134:135]
	ds_read_b128 v[206:209], v142 offset:32768
	ds_read_b128 v[210:213], v142 offset:33792
	ds_read_b128 v[214:217], v142 offset:34816
	ds_read_b128 v[218:221], v142 offset:35840
	ds_read_b128 v[222:225], v142 offset:36864
	ds_read_b128 v[226:229], v142 offset:37888
	ds_read_b128 v[230:233], v142 offset:38912
	ds_read_b128 v[234:237], v142 offset:39936
	global_load_lds_dwordx4 v[248:249], off
	v_lshl_add_u64 v[248:249], s[46:47], 0, v[132:133]
	s_mov_b32 m0, s76
	s_nop 0
	global_load_lds_dwordx4 v[248:249], off
	s_waitcnt vmcnt(8)
	s_waitcnt lgkmcnt(0)
	s_setprio 1
	s_waitcnt lgkmcnt(0)
	v_mfma_f32_16x16x32_bf16 v[126:129], v[144:147], v[206:209], v[126:129]
	v_mfma_f32_16x16x32_bf16 v[122:125], v[152:155], v[206:209], v[122:125]
	v_mfma_f32_16x16x32_bf16 v[118:121], v[144:147], v[214:217], v[118:121]
	v_mfma_f32_16x16x32_bf16 v[114:117], v[152:155], v[214:217], v[114:117]
	s_barrier
	v_mfma_f32_16x16x32_bf16 v[102:105], v[144:147], v[222:225], v[102:105]
	v_mfma_f32_16x16x32_bf16 v[98:101], v[152:155], v[222:225], v[98:101]
	v_mfma_f32_16x16x32_bf16 v[86:89], v[144:147], v[230:233], v[86:89]
	v_mfma_f32_16x16x32_bf16 v[82:85], v[152:155], v[230:233], v[82:85]
	v_mfma_f32_16x16x32_bf16 v[126:129], v[148:151], v[210:213], v[126:129]
	v_mfma_f32_16x16x32_bf16 v[122:125], v[156:159], v[210:213], v[122:125]
	v_mfma_f32_16x16x32_bf16 v[118:121], v[148:151], v[218:221], v[118:121]
	v_mfma_f32_16x16x32_bf16 v[114:117], v[156:159], v[218:221], v[114:117]
	v_mfma_f32_16x16x32_bf16 v[102:105], v[148:151], v[226:229], v[102:105]
	v_mfma_f32_16x16x32_bf16 v[98:101], v[156:159], v[226:229], v[98:101]
	v_mfma_f32_16x16x32_bf16 v[86:89], v[148:151], v[234:237], v[86:89]
	v_mfma_f32_16x16x32_bf16 v[82:85], v[156:159], v[234:237], v[82:85]
	s_setprio 0
	s_setprio 1
	v_mfma_f32_16x16x32_bf16 v[110:113], v[160:163], v[206:209], v[110:113]
	v_mfma_f32_16x16x32_bf16 v[106:109], v[182:185], v[206:209], v[106:109]
	v_mfma_f32_16x16x32_bf16 v[94:97], v[160:163], v[214:217], v[94:97]
	v_mfma_f32_16x16x32_bf16 v[90:93], v[182:185], v[214:217], v[90:93]
	v_mfma_f32_16x16x32_bf16 v[78:81], v[160:163], v[222:225], v[78:81]
	v_mfma_f32_16x16x32_bf16 v[74:77], v[182:185], v[222:225], v[74:77]
	v_mfma_f32_16x16x32_bf16 v[70:73], v[160:163], v[230:233], v[70:73]
	v_mfma_f32_16x16x32_bf16 v[66:69], v[182:185], v[230:233], v[66:69]
	v_mfma_f32_16x16x32_bf16 v[110:113], v[178:181], v[210:213], v[110:113]
	v_mfma_f32_16x16x32_bf16 v[106:109], v[186:189], v[210:213], v[106:109]
	v_mfma_f32_16x16x32_bf16 v[94:97], v[178:181], v[218:221], v[94:97]
	v_mfma_f32_16x16x32_bf16 v[90:93], v[186:189], v[218:221], v[90:93]
	v_mfma_f32_16x16x32_bf16 v[78:81], v[178:181], v[226:229], v[78:81]
	v_mfma_f32_16x16x32_bf16 v[74:77], v[186:189], v[226:229], v[74:77]
	v_mfma_f32_16x16x32_bf16 v[70:73], v[178:181], v[234:237], v[70:73]
	v_mfma_f32_16x16x32_bf16 v[66:69], v[186:189], v[234:237], v[66:69]
	s_barrier
	s_setprio 0
	s_add_i32 s46, s62, s72
	v_lshl_add_u64 v[164:165], v[164:165], 0, s[42:43]
	s_mov_b32 m0, s46
	ds_read_b128 v[206:209], v142 offset:49152
	ds_read_b128 v[210:213], v142 offset:50176
	ds_read_b128 v[214:217], v142 offset:51200
	ds_read_b128 v[218:221], v142 offset:52224
	ds_read_b128 v[222:225], v142 offset:53248
	ds_read_b128 v[226:229], v142 offset:54272
	ds_read_b128 v[230:233], v142 offset:55296
	ds_read_b128 v[234:237], v142 offset:56320
	global_load_lds_dwordx4 v[164:165], off
	s_add_i32 m0, s46, 0x2000
	s_add_u32 s46, s60, 0x20080
	v_lshl_add_u64 v[164:165], v[242:243], 0, s[42:43]
	s_addc_u32 s47, s61, 0
	s_add_i32 s60, s63, s72
	global_load_lds_dwordx4 v[164:165], off
	v_lshl_add_u64 v[164:165], s[46:47], 0, v[166:167]
	s_mov_b32 m0, s60
	s_nop 0
	global_load_lds_dwordx4 v[164:165], off
	v_lshl_add_u64 v[164:165], s[46:47], 0, v[130:131]
	s_add_i32 m0, s60, 0x2000
	s_nop 0
	global_load_lds_dwordx4 v[164:165], off
	v_lshl_add_u64 v[164:165], v[244:245], 0, s[42:43]
	s_mov_b32 m0, s77
	s_nop 0
	global_load_lds_dwordx4 v[164:165], off
	v_lshl_add_u64 v[164:165], v[246:247], 0, s[42:43]
	s_mov_b32 m0, s78
	s_nop 0
	global_load_lds_dwordx4 v[164:165], off
	s_waitcnt vmcnt(8)
	s_waitcnt lgkmcnt(0)
	s_setprio 1
	s_waitcnt lgkmcnt(0)
	v_mfma_f32_16x16x32_bf16 v[62:65], v[144:147], v[206:209], v[62:65]
	v_mfma_f32_16x16x32_bf16 v[58:61], v[152:155], v[206:209], v[58:61]
	v_mfma_f32_16x16x32_bf16 v[54:57], v[144:147], v[214:217], v[54:57]
	v_mfma_f32_16x16x32_bf16 v[50:53], v[152:155], v[214:217], v[50:53]
	s_barrier
	v_mfma_f32_16x16x32_bf16 v[38:41], v[144:147], v[222:225], v[38:41]
	v_mfma_f32_16x16x32_bf16 v[34:37], v[152:155], v[222:225], v[34:37]
	v_mfma_f32_16x16x32_bf16 v[22:25], v[144:147], v[230:233], v[22:25]
	v_mfma_f32_16x16x32_bf16 v[18:21], v[152:155], v[230:233], v[18:21]
	v_mfma_f32_16x16x32_bf16 v[62:65], v[148:151], v[210:213], v[62:65]
	v_mfma_f32_16x16x32_bf16 v[58:61], v[156:159], v[210:213], v[58:61]
	v_mfma_f32_16x16x32_bf16 v[54:57], v[148:151], v[218:221], v[54:57]
	v_mfma_f32_16x16x32_bf16 v[50:53], v[156:159], v[218:221], v[50:53]
	v_mfma_f32_16x16x32_bf16 v[38:41], v[148:151], v[226:229], v[38:41]
	v_mfma_f32_16x16x32_bf16 v[34:37], v[156:159], v[226:229], v[34:37]
	v_mfma_f32_16x16x32_bf16 v[22:25], v[148:151], v[234:237], v[22:25]
	v_mfma_f32_16x16x32_bf16 v[18:21], v[156:159], v[234:237], v[18:21]
	s_setprio 0
	s_setprio 1
	v_mfma_f32_16x16x32_bf16 v[46:49], v[160:163], v[206:209], v[46:49]
	v_mfma_f32_16x16x32_bf16 v[42:45], v[182:185], v[206:209], v[42:45]
	v_mfma_f32_16x16x32_bf16 v[30:33], v[160:163], v[214:217], v[30:33]
	v_mfma_f32_16x16x32_bf16 v[26:29], v[182:185], v[214:217], v[26:29]
	v_mfma_f32_16x16x32_bf16 v[14:17], v[160:163], v[222:225], v[14:17]
	v_mfma_f32_16x16x32_bf16 v[10:13], v[182:185], v[222:225], v[10:13]
	v_mfma_f32_16x16x32_bf16 v[6:9], v[160:163], v[230:233], v[6:9]
	v_mfma_f32_16x16x32_bf16 v[2:5], v[182:185], v[230:233], v[2:5]
	v_mfma_f32_16x16x32_bf16 v[46:49], v[178:181], v[210:213], v[46:49]
	v_mfma_f32_16x16x32_bf16 v[42:45], v[186:189], v[210:213], v[42:45]
	v_mfma_f32_16x16x32_bf16 v[30:33], v[178:181], v[218:221], v[30:33]
	v_mfma_f32_16x16x32_bf16 v[26:29], v[186:189], v[218:221], v[26:29]
	v_mfma_f32_16x16x32_bf16 v[14:17], v[178:181], v[226:229], v[14:17]
	v_mfma_f32_16x16x32_bf16 v[10:13], v[186:189], v[226:229], v[10:13]
	v_mfma_f32_16x16x32_bf16 v[6:9], v[178:181], v[234:237], v[6:9]
	v_mfma_f32_16x16x32_bf16 v[2:5], v[186:189], v[234:237], v[2:5]
	s_barrier
	s_setprio 0
	s_add_i32 s84, s84, 2
	s_add_u32 s66, s66, 0x100
	s_addc_u32 s67, s67, 0
	s_add_u32 s82, s82, 0x100
	s_addc_u32 s83, s83, 0
	s_cmp_gt_u32 s84, 5
	s_cbranch_scc0 .LBB0_426
	s_and_b64 vcc, exec, s[12:13]
	s_cbranch_vccz .LBB0_429
	s_barrier

.LBB0_442:
	s_add_u32 s62, s18, s72
	s_addc_u32 s63, s19, 0
	s_add_u32 s73, s62, 0x100
	s_addc_u32 s74, s63, 0
	s_and_b64 s[46:47], s[60:61], exec
	s_cselect_b32 s75, s23, s74
	s_cselect_b32 s74, s92, s73
	s_add_u32 s46, s16, s72
	s_addc_u32 s47, s17, 0
	s_add_u32 s72, s46, 0x100
	s_addc_u32 s73, s47, 0
	s_add_i32 s48, 0, 0x10000
	s_and_b64 s[46:47], s[60:61], exec
	s_cselect_b32 s77, s21, s73
	s_cselect_b32 s76, s93, s72
	s_add_i32 s46, 0, 0x14000
	s_add_u32 s80, s62, 0x10080
	s_addc_u32 s81, s63, 0
	s_add_i32 s63, s48, s84
	s_add_i32 m0, s13, 0xc000
	s_add_i32 s49, s13, 0xe000
	s_add_i32 vcc_lo, s63, 0x2000
	v_add_u32_e32 v139, s48, v136
	s_add_u32 s78, s76, 0x10000
	ds_read_b128 v[140:143], v139
	ds_read_b128 v[144:147], v139 offset:1024
	ds_read_b128 v[148:151], v139 offset:2048
	ds_read_b128 v[152:155], v139 offset:3072
	v_add_u32_e32 v139, s46, v136
	s_addc_u32 s79, s77, 0
	s_add_i32 vcc_hi, s46, s84
	ds_read_b128 v[156:159], v139
	ds_read_b128 v[160:163], v139 offset:1024
	ds_read_b128 v[178:181], v139 offset:2048
	ds_read_b128 v[182:185], v139 offset:3072
	s_add_i32 s62, vcc_hi, 0x2000
	s_add_i32 s97, 0, 0x18000
	s_add_i32 s96, 0, 0x1c000
	s_add_u32 s72, s74, 0x10000
	s_addc_u32 s73, s75, 0
	s_add_i32 s95, s97, s84
	s_add_i32 s94, s95, 0x2000
	s_add_u32 s60, s76, 0x10080
	s_addc_u32 s61, s77, 0
	s_add_i32 s47, s96, s84
	s_add_i32 s46, s47, 0x2000
	v_lshl_add_u64 v[164:165], s[80:81], 0, v[134:135]
	ds_read_b128 v[186:189], v138
	ds_read_b128 v[206:209], v138 offset:1024
	ds_read_b128 v[210:213], v138 offset:2048
	ds_read_b128 v[214:217], v138 offset:3072
	ds_read_b128 v[218:221], v138 offset:4096
	ds_read_b128 v[222:225], v138 offset:5120
	ds_read_b128 v[226:229], v138 offset:6144
	ds_read_b128 v[230:233], v138 offset:7168
	global_load_lds_dwordx4 v[164:165], off
	v_lshl_add_u64 v[164:165], s[80:81], 0, v[132:133]
	s_mov_b32 m0, s49
	s_nop 0
	global_load_lds_dwordx4 v[164:165], off
	s_waitcnt vmcnt(8)
	s_waitcnt lgkmcnt(0)
	s_setprio 1
	s_waitcnt lgkmcnt(0)
	v_mfma_f32_16x16x32_bf16 v[126:129], v[140:143], v[186:189], v[126:129]
	v_mfma_f32_16x16x32_bf16 v[122:125], v[148:151], v[186:189], v[122:125]
	v_mfma_f32_16x16x32_bf16 v[118:121], v[140:143], v[210:213], v[118:121]
	v_mfma_f32_16x16x32_bf16 v[114:117], v[148:151], v[210:213], v[114:117]
	s_barrier
	v_mfma_f32_16x16x32_bf16 v[102:105], v[140:143], v[218:221], v[102:105]
	v_mfma_f32_16x16x32_bf16 v[98:101], v[148:151], v[218:221], v[98:101]
	v_mfma_f32_16x16x32_bf16 v[86:89], v[140:143], v[226:229], v[86:89]
	v_mfma_f32_16x16x32_bf16 v[82:85], v[148:151], v[226:229], v[82:85]
	v_mfma_f32_16x16x32_bf16 v[126:129], v[144:147], v[206:209], v[126:129]
	v_mfma_f32_16x16x32_bf16 v[122:125], v[152:155], v[206:209], v[122:125]
	v_mfma_f32_16x16x32_bf16 v[118:121], v[144:147], v[214:217], v[118:121]
	v_mfma_f32_16x16x32_bf16 v[114:117], v[152:155], v[214:217], v[114:117]
	v_mfma_f32_16x16x32_bf16 v[102:105], v[144:147], v[222:225], v[102:105]
	v_mfma_f32_16x16x32_bf16 v[98:101], v[152:155], v[222:225], v[98:101]
	v_mfma_f32_16x16x32_bf16 v[86:89], v[144:147], v[230:233], v[86:89]
	v_mfma_f32_16x16x32_bf16 v[82:85], v[152:155], v[230:233], v[82:85]
	s_setprio 0
	s_setprio 1
	v_mfma_f32_16x16x32_bf16 v[110:113], v[156:159], v[186:189], v[110:113]
	v_mfma_f32_16x16x32_bf16 v[106:109], v[178:181], v[186:189], v[106:109]
	v_mfma_f32_16x16x32_bf16 v[94:97], v[156:159], v[210:213], v[94:97]
	v_mfma_f32_16x16x32_bf16 v[90:93], v[178:181], v[210:213], v[90:93]
	v_mfma_f32_16x16x32_bf16 v[78:81], v[156:159], v[218:221], v[78:81]
	v_mfma_f32_16x16x32_bf16 v[74:77], v[178:181], v[218:221], v[74:77]
	v_mfma_f32_16x16x32_bf16 v[70:73], v[156:159], v[226:229], v[70:73]
	v_mfma_f32_16x16x32_bf16 v[66:69], v[178:181], v[226:229], v[66:69]
	v_mfma_f32_16x16x32_bf16 v[110:113], v[160:163], v[206:209], v[110:113]
	v_mfma_f32_16x16x32_bf16 v[106:109], v[182:185], v[206:209], v[106:109]
	v_mfma_f32_16x16x32_bf16 v[94:97], v[160:163], v[214:217], v[94:97]
	v_mfma_f32_16x16x32_bf16 v[90:93], v[182:185], v[214:217], v[90:93]
	v_mfma_f32_16x16x32_bf16 v[78:81], v[160:163], v[222:225], v[78:81]
	v_mfma_f32_16x16x32_bf16 v[74:77], v[182:185], v[222:225], v[74:77]
	v_mfma_f32_16x16x32_bf16 v[70:73], v[160:163], v[230:233], v[70:73]
	v_mfma_f32_16x16x32_bf16 v[66:69], v[182:185], v[230:233], v[66:69]
	s_barrier
	s_setprio 0
	s_mov_b32 m0, s63
	v_lshl_add_u64 v[164:165], s[76:77], 0, v[166:167]
	ds_read_b128 v[186:189], v138 offset:16384
	ds_read_b128 v[206:209], v138 offset:17408
	ds_read_b128 v[210:213], v138 offset:18432
	ds_read_b128 v[214:217], v138 offset:19456
	ds_read_b128 v[218:221], v138 offset:20480
	ds_read_b128 v[222:225], v138 offset:21504
	ds_read_b128 v[226:229], v138 offset:22528
	ds_read_b128 v[230:233], v138 offset:23552
	global_load_lds_dwordx4 v[164:165], off
	v_lshl_add_u64 v[234:235], s[76:77], 0, v[130:131]
	s_mov_b32 m0, vcc_lo
	v_lshl_add_u64 v[236:237], s[78:79], 0, v[166:167]
	global_load_lds_dwordx4 v[234:235], off
	s_mov_b32 m0, vcc_hi
	v_lshl_add_u64 v[242:243], s[74:75], 0, v[132:133]
	global_load_lds_dwordx4 v[236:237], off
	v_lshl_add_u64 v[236:237], s[78:79], 0, v[130:131]
	s_mov_b32 m0, s62
	s_nop 0
	global_load_lds_dwordx4 v[236:237], off
	v_lshl_add_u64 v[236:237], s[74:75], 0, v[134:135]
	s_mov_b32 m0, s13
	s_nop 0
	global_load_lds_dwordx4 v[236:237], off
	s_mov_b32 m0, s86
	s_nop 0
	global_load_lds_dwordx4 v[242:243], off
	s_waitcnt vmcnt(8)
	s_waitcnt lgkmcnt(0)
	s_setprio 1
	s_waitcnt lgkmcnt(0)
	v_mfma_f32_16x16x32_bf16 v[62:65], v[140:143], v[186:189], v[62:65]
	v_mfma_f32_16x16x32_bf16 v[58:61], v[148:151], v[186:189], v[58:61]
	v_mfma_f32_16x16x32_bf16 v[54:57], v[140:143], v[210:213], v[54:57]
	v_mfma_f32_16x16x32_bf16 v[50:53], v[148:151], v[210:213], v[50:53]
	s_barrier
	v_mfma_f32_16x16x32_bf16 v[38:41], v[140:143], v[218:221], v[38:41]
	v_mfma_f32_16x16x32_bf16 v[34:37], v[148:151], v[218:221], v[34:37]
	v_mfma_f32_16x16x32_bf16 v[22:25], v[140:143], v[226:229], v[22:25]
	v_mfma_f32_16x16x32_bf16 v[18:21], v[148:151], v[226:229], v[18:21]
	v_mfma_f32_16x16x32_bf16 v[62:65], v[144:147], v[206:209], v[62:65]
	v_mfma_f32_16x16x32_bf16 v[58:61], v[152:155], v[206:209], v[58:61]
	v_mfma_f32_16x16x32_bf16 v[54:57], v[144:147], v[214:217], v[54:57]
	v_mfma_f32_16x16x32_bf16 v[50:53], v[152:155], v[214:217], v[50:53]
	v_mfma_f32_16x16x32_bf16 v[38:41], v[144:147], v[222:225], v[38:41]
	v_mfma_f32_16x16x32_bf16 v[34:37], v[152:155], v[222:225], v[34:37]
	v_mfma_f32_16x16x32_bf16 v[22:25], v[144:147], v[230:233], v[22:25]
	v_mfma_f32_16x16x32_bf16 v[18:21], v[152:155], v[230:233], v[18:21]
	s_setprio 0
	s_setprio 1
	v_mfma_f32_16x16x32_bf16 v[46:49], v[156:159], v[186:189], v[46:49]
	v_mfma_f32_16x16x32_bf16 v[42:45], v[178:181], v[186:189], v[42:45]
	v_mfma_f32_16x16x32_bf16 v[30:33], v[156:159], v[210:213], v[30:33]
	v_mfma_f32_16x16x32_bf16 v[26:29], v[178:181], v[210:213], v[26:29]
	v_mfma_f32_16x16x32_bf16 v[14:17], v[156:159], v[218:221], v[14:17]
	v_mfma_f32_16x16x32_bf16 v[10:13], v[178:181], v[218:221], v[10:13]
	v_mfma_f32_16x16x32_bf16 v[6:9], v[156:159], v[226:229], v[6:9]
	v_mfma_f32_16x16x32_bf16 v[2:5], v[178:181], v[226:229], v[2:5]
	v_mfma_f32_16x16x32_bf16 v[46:49], v[160:163], v[206:209], v[46:49]
	v_mfma_f32_16x16x32_bf16 v[42:45], v[182:185], v[206:209], v[42:45]
	v_mfma_f32_16x16x32_bf16 v[30:33], v[160:163], v[214:217], v[30:33]
	v_mfma_f32_16x16x32_bf16 v[26:29], v[182:185], v[214:217], v[26:29]
	v_mfma_f32_16x16x32_bf16 v[14:17], v[160:163], v[222:225], v[14:17]
	v_mfma_f32_16x16x32_bf16 v[10:13], v[182:185], v[222:225], v[10:13]
	v_mfma_f32_16x16x32_bf16 v[6:9], v[160:163], v[230:233], v[6:9]
	v_mfma_f32_16x16x32_bf16 v[2:5], v[182:185], v[230:233], v[2:5]
	s_barrier
	s_setprio 0
	v_add_u32_e32 v139, s97, v136
	ds_read_b128 v[140:143], v139
	ds_read_b128 v[144:147], v139 offset:1024
	ds_read_b128 v[148:151], v139 offset:2048
	ds_read_b128 v[152:155], v139 offset:3072
	v_add_u32_e32 v139, s96, v136
	ds_read_b128 v[156:159], v139
	ds_read_b128 v[160:163], v139 offset:1024
	ds_read_b128 v[178:181], v139 offset:2048
	ds_read_b128 v[182:185], v139 offset:3072
	s_mov_b32 m0, s87
	v_lshl_add_u64 v[244:245], s[72:73], 0, v[134:135]
	ds_read_b128 v[186:189], v138 offset:32768
	ds_read_b128 v[206:209], v138 offset:33792
	ds_read_b128 v[210:213], v138 offset:34816
	ds_read_b128 v[214:217], v138 offset:35840
	ds_read_b128 v[218:221], v138 offset:36864
	ds_read_b128 v[222:225], v138 offset:37888
	ds_read_b128 v[226:229], v138 offset:38912
	ds_read_b128 v[230:233], v138 offset:39936
	global_load_lds_dwordx4 v[244:245], off
	v_lshl_add_u64 v[244:245], s[72:73], 0, v[132:133]
	s_mov_b32 m0, s88
	s_nop 0
	global_load_lds_dwordx4 v[244:245], off
	s_waitcnt vmcnt(8)
	s_waitcnt lgkmcnt(0)
	s_setprio 1
	s_waitcnt lgkmcnt(0)
	v_mfma_f32_16x16x32_bf16 v[126:129], v[140:143], v[186:189], v[126:129]
	v_mfma_f32_16x16x32_bf16 v[122:125], v[148:151], v[186:189], v[122:125]
	v_mfma_f32_16x16x32_bf16 v[118:121], v[140:143], v[210:213], v[118:121]
	v_mfma_f32_16x16x32_bf16 v[114:117], v[148:151], v[210:213], v[114:117]
	s_barrier
	v_mfma_f32_16x16x32_bf16 v[102:105], v[140:143], v[218:221], v[102:105]
	v_mfma_f32_16x16x32_bf16 v[98:101], v[148:151], v[218:221], v[98:101]
	v_mfma_f32_16x16x32_bf16 v[86:89], v[140:143], v[226:229], v[86:89]
	v_mfma_f32_16x16x32_bf16 v[82:85], v[148:151], v[226:229], v[82:85]
	v_mfma_f32_16x16x32_bf16 v[126:129], v[144:147], v[206:209], v[126:129]
	v_mfma_f32_16x16x32_bf16 v[122:125], v[152:155], v[206:209], v[122:125]
	v_mfma_f32_16x16x32_bf16 v[118:121], v[144:147], v[214:217], v[118:121]
	v_mfma_f32_16x16x32_bf16 v[114:117], v[152:155], v[214:217], v[114:117]
	v_mfma_f32_16x16x32_bf16 v[102:105], v[144:147], v[222:225], v[102:105]
	v_mfma_f32_16x16x32_bf16 v[98:101], v[152:155], v[222:225], v[98:101]
	v_mfma_f32_16x16x32_bf16 v[86:89], v[144:147], v[230:233], v[86:89]
	v_mfma_f32_16x16x32_bf16 v[82:85], v[152:155], v[230:233], v[82:85]
	s_setprio 0
	s_setprio 1
	v_mfma_f32_16x16x32_bf16 v[110:113], v[156:159], v[186:189], v[110:113]
	v_mfma_f32_16x16x32_bf16 v[106:109], v[178:181], v[186:189], v[106:109]
	v_mfma_f32_16x16x32_bf16 v[94:97], v[156:159], v[210:213], v[94:97]
	v_mfma_f32_16x16x32_bf16 v[90:93], v[178:181], v[210:213], v[90:93]
	v_mfma_f32_16x16x32_bf16 v[78:81], v[156:159], v[218:221], v[78:81]
	v_mfma_f32_16x16x32_bf16 v[74:77], v[178:181], v[218:221], v[74:77]
	v_mfma_f32_16x16x32_bf16 v[70:73], v[156:159], v[226:229], v[70:73]
	v_mfma_f32_16x16x32_bf16 v[66:69], v[178:181], v[226:229], v[66:69]
	v_mfma_f32_16x16x32_bf16 v[110:113], v[160:163], v[206:209], v[110:113]
	v_mfma_f32_16x16x32_bf16 v[106:109], v[182:185], v[206:209], v[106:109]
	v_mfma_f32_16x16x32_bf16 v[94:97], v[160:163], v[214:217], v[94:97]
	v_mfma_f32_16x16x32_bf16 v[90:93], v[182:185], v[214:217], v[90:93]
	v_mfma_f32_16x16x32_bf16 v[78:81], v[160:163], v[222:225], v[78:81]
	v_mfma_f32_16x16x32_bf16 v[74:77], v[182:185], v[222:225], v[74:77]
	v_mfma_f32_16x16x32_bf16 v[70:73], v[160:163], v[230:233], v[70:73]
	v_mfma_f32_16x16x32_bf16 v[66:69], v[182:185], v[230:233], v[66:69]
	s_barrier
	s_setprio 0
	s_mov_b32 m0, s95
	v_lshl_add_u64 v[164:165], v[164:165], 0, s[42:43]
	ds_read_b128 v[186:189], v138 offset:49152
	ds_read_b128 v[206:209], v138 offset:50176
	ds_read_b128 v[210:213], v138 offset:51200
	ds_read_b128 v[214:217], v138 offset:52224
	ds_read_b128 v[218:221], v138 offset:53248
	ds_read_b128 v[222:225], v138 offset:54272
	ds_read_b128 v[226:229], v138 offset:55296
	ds_read_b128 v[230:233], v138 offset:56320
	global_load_lds_dwordx4 v[164:165], off
	v_lshl_add_u64 v[164:165], v[234:235], 0, s[42:43]
	s_mov_b32 m0, s94
	s_nop 0
	global_load_lds_dwordx4 v[164:165], off
	v_lshl_add_u64 v[164:165], s[60:61], 0, v[166:167]
	s_mov_b32 m0, s47
	s_nop 0
	global_load_lds_dwordx4 v[164:165], off
	v_lshl_add_u64 v[164:165], s[60:61], 0, v[130:131]
	s_mov_b32 m0, s46
	s_nop 0
	global_load_lds_dwordx4 v[164:165], off
	v_lshl_add_u64 v[164:165], v[236:237], 0, s[42:43]
	s_mov_b32 m0, s89
	s_nop 0
	global_load_lds_dwordx4 v[164:165], off
	v_lshl_add_u64 v[164:165], v[242:243], 0, s[42:43]
	s_mov_b32 m0, s90
	s_nop 0
	global_load_lds_dwordx4 v[164:165], off
	s_waitcnt vmcnt(8)
	s_waitcnt lgkmcnt(0)
	s_setprio 1
	s_waitcnt lgkmcnt(0)
	v_mfma_f32_16x16x32_bf16 v[62:65], v[140:143], v[186:189], v[62:65]
	v_mfma_f32_16x16x32_bf16 v[58:61], v[148:151], v[186:189], v[58:61]
	v_mfma_f32_16x16x32_bf16 v[54:57], v[140:143], v[210:213], v[54:57]
	v_mfma_f32_16x16x32_bf16 v[50:53], v[148:151], v[210:213], v[50:53]
	s_barrier
	v_mfma_f32_16x16x32_bf16 v[38:41], v[140:143], v[218:221], v[38:41]
	v_mfma_f32_16x16x32_bf16 v[34:37], v[148:151], v[218:221], v[34:37]
	v_mfma_f32_16x16x32_bf16 v[22:25], v[140:143], v[226:229], v[22:25]
	v_mfma_f32_16x16x32_bf16 v[18:21], v[148:151], v[226:229], v[18:21]
	v_mfma_f32_16x16x32_bf16 v[62:65], v[144:147], v[206:209], v[62:65]
	v_mfma_f32_16x16x32_bf16 v[58:61], v[152:155], v[206:209], v[58:61]
	v_mfma_f32_16x16x32_bf16 v[54:57], v[144:147], v[214:217], v[54:57]
	v_mfma_f32_16x16x32_bf16 v[50:53], v[152:155], v[214:217], v[50:53]
	v_mfma_f32_16x16x32_bf16 v[38:41], v[144:147], v[222:225], v[38:41]
	v_mfma_f32_16x16x32_bf16 v[34:37], v[152:155], v[222:225], v[34:37]
	v_mfma_f32_16x16x32_bf16 v[22:25], v[144:147], v[230:233], v[22:25]
	v_mfma_f32_16x16x32_bf16 v[18:21], v[152:155], v[230:233], v[18:21]
	s_setprio 0
	s_setprio 1
	v_mfma_f32_16x16x32_bf16 v[46:49], v[156:159], v[186:189], v[46:49]
	v_mfma_f32_16x16x32_bf16 v[42:45], v[178:181], v[186:189], v[42:45]
	v_mfma_f32_16x16x32_bf16 v[30:33], v[156:159], v[210:213], v[30:33]
	v_mfma_f32_16x16x32_bf16 v[26:29], v[178:181], v[210:213], v[26:29]
	v_mfma_f32_16x16x32_bf16 v[14:17], v[156:159], v[218:221], v[14:17]
	v_mfma_f32_16x16x32_bf16 v[10:13], v[178:181], v[218:221], v[10:13]
	v_mfma_f32_16x16x32_bf16 v[6:9], v[156:159], v[226:229], v[6:9]
	v_mfma_f32_16x16x32_bf16 v[2:5], v[178:181], v[226:229], v[2:5]
	v_mfma_f32_16x16x32_bf16 v[46:49], v[160:163], v[206:209], v[46:49]
	v_mfma_f32_16x16x32_bf16 v[42:45], v[182:185], v[206:209], v[42:45]
	v_mfma_f32_16x16x32_bf16 v[30:33], v[160:163], v[214:217], v[30:33]
	v_mfma_f32_16x16x32_bf16 v[26:29], v[182:185], v[214:217], v[26:29]
	v_mfma_f32_16x16x32_bf16 v[14:17], v[160:163], v[222:225], v[14:17]
	v_mfma_f32_16x16x32_bf16 v[10:13], v[182:185], v[222:225], v[10:13]
	v_mfma_f32_16x16x32_bf16 v[6:9], v[160:163], v[230:233], v[6:9]
	v_mfma_f32_16x16x32_bf16 v[2:5], v[182:185], v[230:233], v[2:5]
	s_barrier
	s_setprio 0
	s_movk_i32 s72, 0x100
	s_andn2_b64 vcc, exec, s[70:71]
	s_mov_b64 s[60:61], -1
	s_mov_b64 s[70:71], 0
	s_cbranch_vccz .LBB0_442
	s_and_b64 vcc, exec, s[10:11]
	s_cbranch_vccz .LBB0_445
	s_barrier

.LBB0_795:
	s_add_u32 s46, s68, 0xfff80080
	s_addc_u32 s47, s69, -1
	s_add_i32 s48, 0, 0x10000
	s_cmp_eq_u32 s87, 28
	s_cselect_b32 s71, s19, s47
	s_cselect_b32 s70, s83, s46
	s_cselect_b32 s61, s17, s86
	s_cselect_b32 s60, s84, s85
	s_add_i32 s49, 0, 0x14000
	v_add_u32_e32 v156, s48, v1
	v_add_u32_e32 v164, s49, v1
	ds_read_b128 v[130:133], v156
	ds_read_b128 v[134:137], v156 offset:1024
	ds_read_b128 v[150:153], v156 offset:2048
	ds_read_b128 v[156:159], v156 offset:3072
	ds_read_b128 v[160:163], v164
	ds_read_b128 v[178:181], v164 offset:1024
	ds_read_b128 v[182:185], v164 offset:2048
	ds_read_b128 v[186:189], v164 offset:3072
	v_lshl_add_u64 v[164:165], s[68:69], 0, v[146:147]
	s_add_i32 m0, s67, 0xc000
	ds_read_b128 v[206:209], v155
	ds_read_b128 v[210:213], v155 offset:1024
	ds_read_b128 v[214:217], v155 offset:2048
	ds_read_b128 v[218:221], v155 offset:3072
	ds_read_b128 v[222:225], v155 offset:4096
	ds_read_b128 v[226:229], v155 offset:5120
	ds_read_b128 v[230:233], v155 offset:6144
	ds_read_b128 v[234:237], v155 offset:7168
	global_load_lds_dwordx4 v[164:165], off
	v_lshl_add_u64 v[164:165], s[68:69], 0, v[148:149]
	s_add_i32 m0, s67, 0xe000
	s_nop 0
	global_load_lds_dwordx4 v[164:165], off
	s_waitcnt vmcnt(8)
	s_waitcnt lgkmcnt(0)
	s_setprio 1
	s_waitcnt lgkmcnt(0)
	v_mfma_f32_16x16x32_bf16 v[126:129], v[130:133], v[206:209], v[126:129]
	v_mfma_f32_16x16x32_bf16 v[122:125], v[150:153], v[206:209], v[122:125]
	v_mfma_f32_16x16x32_bf16 v[118:121], v[130:133], v[214:217], v[118:121]
	v_mfma_f32_16x16x32_bf16 v[114:117], v[150:153], v[214:217], v[114:117]
	s_barrier
	v_mfma_f32_16x16x32_bf16 v[110:113], v[130:133], v[222:225], v[110:113]
	v_mfma_f32_16x16x32_bf16 v[106:109], v[150:153], v[222:225], v[106:109]
	v_mfma_f32_16x16x32_bf16 v[102:105], v[130:133], v[230:233], v[102:105]
	v_mfma_f32_16x16x32_bf16 v[98:101], v[150:153], v[230:233], v[98:101]
	v_mfma_f32_16x16x32_bf16 v[126:129], v[134:137], v[210:213], v[126:129]
	v_mfma_f32_16x16x32_bf16 v[122:125], v[156:159], v[210:213], v[122:125]
	v_mfma_f32_16x16x32_bf16 v[118:121], v[134:137], v[218:221], v[118:121]
	v_mfma_f32_16x16x32_bf16 v[114:117], v[156:159], v[218:221], v[114:117]
	v_mfma_f32_16x16x32_bf16 v[110:113], v[134:137], v[226:229], v[110:113]
	v_mfma_f32_16x16x32_bf16 v[106:109], v[156:159], v[226:229], v[106:109]
	v_mfma_f32_16x16x32_bf16 v[102:105], v[134:137], v[234:237], v[102:105]
	v_mfma_f32_16x16x32_bf16 v[98:101], v[156:159], v[234:237], v[98:101]
	s_setprio 0
	s_setprio 1
	v_mfma_f32_16x16x32_bf16 v[66:69], v[160:163], v[206:209], v[66:69]
	v_mfma_f32_16x16x32_bf16 v[58:61], v[182:185], v[206:209], v[58:61]
	v_mfma_f32_16x16x32_bf16 v[54:57], v[160:163], v[214:217], v[54:57]
	v_mfma_f32_16x16x32_bf16 v[50:53], v[182:185], v[214:217], v[50:53]
	v_mfma_f32_16x16x32_bf16 v[46:49], v[160:163], v[222:225], v[46:49]
	v_mfma_f32_16x16x32_bf16 v[42:45], v[182:185], v[222:225], v[42:45]
	v_mfma_f32_16x16x32_bf16 v[38:41], v[160:163], v[230:233], v[38:41]
	v_mfma_f32_16x16x32_bf16 v[34:37], v[182:185], v[230:233], v[34:37]
	v_mfma_f32_16x16x32_bf16 v[66:69], v[178:181], v[210:213], v[66:69]
	v_mfma_f32_16x16x32_bf16 v[58:61], v[186:189], v[210:213], v[58:61]
	v_mfma_f32_16x16x32_bf16 v[54:57], v[178:181], v[218:221], v[54:57]
	v_mfma_f32_16x16x32_bf16 v[50:53], v[186:189], v[218:221], v[50:53]
	v_mfma_f32_16x16x32_bf16 v[46:49], v[178:181], v[226:229], v[46:49]
	v_mfma_f32_16x16x32_bf16 v[42:45], v[186:189], v[226:229], v[42:45]
	v_mfma_f32_16x16x32_bf16 v[38:41], v[178:181], v[234:237], v[38:41]
	v_mfma_f32_16x16x32_bf16 v[34:37], v[186:189], v[234:237], v[34:37]
	s_barrier
	s_setprio 0
	s_add_i32 s46, s48, s77
	v_lshl_add_u64 v[164:165], s[60:61], 0, v[166:167]
	s_mov_b32 m0, s46
	ds_read_b128 v[206:209], v155 offset:16384
	ds_read_b128 v[210:213], v155 offset:17408
	ds_read_b128 v[214:217], v155 offset:18432
	ds_read_b128 v[218:221], v155 offset:19456
	ds_read_b128 v[222:225], v155 offset:20480
	ds_read_b128 v[226:229], v155 offset:21504
	ds_read_b128 v[230:233], v155 offset:22528
	ds_read_b128 v[234:237], v155 offset:23552
	global_load_lds_dwordx4 v[164:165], off
	s_add_i32 m0, s46, 0x2000
	s_add_u32 s46, s60, 0x80000
	v_lshl_add_u64 v[242:243], s[60:61], 0, v[142:143]
	s_addc_u32 s47, s61, 0
	s_add_i32 s48, s49, s77
	global_load_lds_dwordx4 v[242:243], off
	v_lshl_add_u64 v[244:245], s[46:47], 0, v[166:167]
	s_mov_b32 m0, s48
	v_lshl_add_u64 v[246:247], s[70:71], 0, v[140:141]
	global_load_lds_dwordx4 v[244:245], off
	v_lshl_add_u64 v[244:245], s[46:47], 0, v[142:143]
	s_add_i32 m0, s48, 0x2000
	s_nop 0
	global_load_lds_dwordx4 v[244:245], off
	v_lshl_add_u64 v[244:245], s[70:71], 0, v[138:139]
	s_mov_b32 m0, s67
	s_nop 0
	global_load_lds_dwordx4 v[244:245], off
	s_mov_b32 m0, s78
	s_nop 0
	global_load_lds_dwordx4 v[246:247], off
	s_waitcnt vmcnt(8)
	s_waitcnt lgkmcnt(0)
	s_setprio 1
	s_waitcnt lgkmcnt(0)
	v_mfma_f32_16x16x32_bf16 v[94:97], v[130:133], v[206:209], v[94:97]
	v_mfma_f32_16x16x32_bf16 v[90:93], v[150:153], v[206:209], v[90:93]
	v_mfma_f32_16x16x32_bf16 v[86:89], v[130:133], v[214:217], v[86:89]
	v_mfma_f32_16x16x32_bf16 v[82:85], v[150:153], v[214:217], v[82:85]
	s_barrier
	v_mfma_f32_16x16x32_bf16 v[78:81], v[130:133], v[222:225], v[78:81]
	v_mfma_f32_16x16x32_bf16 v[74:77], v[150:153], v[222:225], v[74:77]
	v_mfma_f32_16x16x32_bf16 v[70:73], v[130:133], v[230:233], v[70:73]
	v_mfma_f32_16x16x32_bf16 v[62:65], v[150:153], v[230:233], v[62:65]
	v_mfma_f32_16x16x32_bf16 v[94:97], v[134:137], v[210:213], v[94:97]
	v_mfma_f32_16x16x32_bf16 v[90:93], v[156:159], v[210:213], v[90:93]
	v_mfma_f32_16x16x32_bf16 v[86:89], v[134:137], v[218:221], v[86:89]
	v_mfma_f32_16x16x32_bf16 v[82:85], v[156:159], v[218:221], v[82:85]
	v_mfma_f32_16x16x32_bf16 v[78:81], v[134:137], v[226:229], v[78:81]
	v_mfma_f32_16x16x32_bf16 v[74:77], v[156:159], v[226:229], v[74:77]
	v_mfma_f32_16x16x32_bf16 v[70:73], v[134:137], v[234:237], v[70:73]
	v_mfma_f32_16x16x32_bf16 v[62:65], v[156:159], v[234:237], v[62:65]
	s_setprio 0
	s_setprio 1
	v_mfma_f32_16x16x32_bf16 v[30:33], v[160:163], v[206:209], v[30:33]
	v_mfma_f32_16x16x32_bf16 v[26:29], v[182:185], v[206:209], v[26:29]
	v_mfma_f32_16x16x32_bf16 v[22:25], v[160:163], v[214:217], v[22:25]
	v_mfma_f32_16x16x32_bf16 v[18:21], v[182:185], v[214:217], v[18:21]
	v_mfma_f32_16x16x32_bf16 v[14:17], v[160:163], v[222:225], v[14:17]
	v_mfma_f32_16x16x32_bf16 v[10:13], v[182:185], v[222:225], v[10:13]
	v_mfma_f32_16x16x32_bf16 v[6:9], v[160:163], v[230:233], v[6:9]
	v_mfma_f32_16x16x32_bf16 v[2:5], v[182:185], v[230:233], v[2:5]
	v_mfma_f32_16x16x32_bf16 v[30:33], v[178:181], v[210:213], v[30:33]
	v_mfma_f32_16x16x32_bf16 v[26:29], v[186:189], v[210:213], v[26:29]
	v_mfma_f32_16x16x32_bf16 v[22:25], v[178:181], v[218:221], v[22:25]
	v_mfma_f32_16x16x32_bf16 v[18:21], v[186:189], v[218:221], v[18:21]
	v_mfma_f32_16x16x32_bf16 v[14:17], v[178:181], v[226:229], v[14:17]
	v_mfma_f32_16x16x32_bf16 v[10:13], v[186:189], v[226:229], v[10:13]
	v_mfma_f32_16x16x32_bf16 v[6:9], v[178:181], v[234:237], v[6:9]
	v_mfma_f32_16x16x32_bf16 v[2:5], v[186:189], v[234:237], v[2:5]
	s_barrier
	s_setprio 0
	s_add_i32 s48, 0, 0x18000
	s_add_i32 s49, 0, 0x1c000
	v_add_u32_e32 v156, s48, v1
	v_add_u32_e32 v186, s49, v1
	ds_read_b128 v[130:133], v156
	ds_read_b128 v[134:137], v156 offset:1024
	ds_read_b128 v[150:153], v156 offset:2048
	ds_read_b128 v[156:159], v156 offset:3072
	ds_read_b128 v[160:163], v186
	ds_read_b128 v[178:181], v186 offset:1024
	ds_read_b128 v[182:185], v186 offset:2048
	ds_read_b128 v[186:189], v186 offset:3072
	s_add_u32 s46, s70, 0x80000
	s_addc_u32 s47, s71, 0
	s_mov_b32 m0, s79
	v_lshl_add_u64 v[248:249], s[46:47], 0, v[138:139]
	ds_read_b128 v[206:209], v155 offset:32768
	ds_read_b128 v[210:213], v155 offset:33792
	ds_read_b128 v[214:217], v155 offset:34816
	ds_read_b128 v[218:221], v155 offset:35840
	ds_read_b128 v[222:225], v155 offset:36864
	ds_read_b128 v[226:229], v155 offset:37888
	ds_read_b128 v[230:233], v155 offset:38912
	ds_read_b128 v[234:237], v155 offset:39936
	global_load_lds_dwordx4 v[248:249], off
	v_lshl_add_u64 v[248:249], s[46:47], 0, v[140:141]
	s_mov_b32 m0, s80
	s_nop 0
	global_load_lds_dwordx4 v[248:249], off
	s_waitcnt vmcnt(8)
	s_waitcnt lgkmcnt(0)
	s_setprio 1
	s_waitcnt lgkmcnt(0)
	v_mfma_f32_16x16x32_bf16 v[126:129], v[130:133], v[206:209], v[126:129]
	v_mfma_f32_16x16x32_bf16 v[122:125], v[150:153], v[206:209], v[122:125]
	v_mfma_f32_16x16x32_bf16 v[118:121], v[130:133], v[214:217], v[118:121]
	v_mfma_f32_16x16x32_bf16 v[114:117], v[150:153], v[214:217], v[114:117]
	s_barrier
	v_mfma_f32_16x16x32_bf16 v[110:113], v[130:133], v[222:225], v[110:113]
	v_mfma_f32_16x16x32_bf16 v[106:109], v[150:153], v[222:225], v[106:109]
	v_mfma_f32_16x16x32_bf16 v[102:105], v[130:133], v[230:233], v[102:105]
	v_mfma_f32_16x16x32_bf16 v[98:101], v[150:153], v[230:233], v[98:101]
	v_mfma_f32_16x16x32_bf16 v[126:129], v[134:137], v[210:213], v[126:129]
	v_mfma_f32_16x16x32_bf16 v[122:125], v[156:159], v[210:213], v[122:125]
	v_mfma_f32_16x16x32_bf16 v[118:121], v[134:137], v[218:221], v[118:121]
	v_mfma_f32_16x16x32_bf16 v[114:117], v[156:159], v[218:221], v[114:117]
	v_mfma_f32_16x16x32_bf16 v[110:113], v[134:137], v[226:229], v[110:113]
	v_mfma_f32_16x16x32_bf16 v[106:109], v[156:159], v[226:229], v[106:109]
	v_mfma_f32_16x16x32_bf16 v[102:105], v[134:137], v[234:237], v[102:105]
	v_mfma_f32_16x16x32_bf16 v[98:101], v[156:159], v[234:237], v[98:101]
	s_setprio 0
	s_setprio 1
	v_mfma_f32_16x16x32_bf16 v[66:69], v[160:163], v[206:209], v[66:69]
	v_mfma_f32_16x16x32_bf16 v[58:61], v[182:185], v[206:209], v[58:61]
	v_mfma_f32_16x16x32_bf16 v[54:57], v[160:163], v[214:217], v[54:57]
	v_mfma_f32_16x16x32_bf16 v[50:53], v[182:185], v[214:217], v[50:53]
	v_mfma_f32_16x16x32_bf16 v[46:49], v[160:163], v[222:225], v[46:49]
	v_mfma_f32_16x16x32_bf16 v[42:45], v[182:185], v[222:225], v[42:45]
	v_mfma_f32_16x16x32_bf16 v[38:41], v[160:163], v[230:233], v[38:41]
	v_mfma_f32_16x16x32_bf16 v[34:37], v[182:185], v[230:233], v[34:37]
	v_mfma_f32_16x16x32_bf16 v[66:69], v[178:181], v[210:213], v[66:69]
	v_mfma_f32_16x16x32_bf16 v[58:61], v[186:189], v[210:213], v[58:61]
	v_mfma_f32_16x16x32_bf16 v[54:57], v[178:181], v[218:221], v[54:57]
	v_mfma_f32_16x16x32_bf16 v[50:53], v[186:189], v[218:221], v[50:53]
	v_mfma_f32_16x16x32_bf16 v[46:49], v[178:181], v[226:229], v[46:49]
	v_mfma_f32_16x16x32_bf16 v[42:45], v[186:189], v[226:229], v[42:45]
	v_mfma_f32_16x16x32_bf16 v[38:41], v[178:181], v[234:237], v[38:41]
	v_mfma_f32_16x16x32_bf16 v[34:37], v[186:189], v[234:237], v[34:37]
	s_barrier
	s_setprio 0
	s_add_i32 s46, s48, s77
	v_lshl_add_u64 v[164:165], v[164:165], 0, s[42:43]
	s_mov_b32 m0, s46
	ds_read_b128 v[206:209], v155 offset:49152
	ds_read_b128 v[210:213], v155 offset:50176
	ds_read_b128 v[214:217], v155 offset:51200
	ds_read_b128 v[218:221], v155 offset:52224
	ds_read_b128 v[222:225], v155 offset:53248
	ds_read_b128 v[226:229], v155 offset:54272
	ds_read_b128 v[230:233], v155 offset:55296
	ds_read_b128 v[234:237], v155 offset:56320
	global_load_lds_dwordx4 v[164:165], off
	s_add_i32 m0, s46, 0x2000
	s_add_u32 s46, s60, 0x80080
	v_lshl_add_u64 v[164:165], v[242:243], 0, s[42:43]
	s_addc_u32 s47, s61, 0
	s_add_i32 s48, s49, s77
	global_load_lds_dwordx4 v[164:165], off
	v_lshl_add_u64 v[164:165], s[46:47], 0, v[166:167]
	s_mov_b32 m0, s48
	s_nop 0
	global_load_lds_dwordx4 v[164:165], off
	v_lshl_add_u64 v[164:165], s[46:47], 0, v[142:143]
	s_add_i32 m0, s48, 0x2000
	s_nop 0
	global_load_lds_dwordx4 v[164:165], off
	v_lshl_add_u64 v[164:165], v[244:245], 0, s[42:43]
	s_mov_b32 m0, s26
	s_nop 0
	global_load_lds_dwordx4 v[164:165], off
	v_lshl_add_u64 v[164:165], v[246:247], 0, s[42:43]
	s_mov_b32 m0, s81
	s_nop 0
	global_load_lds_dwordx4 v[164:165], off
	s_waitcnt vmcnt(8)
	s_waitcnt lgkmcnt(0)
	s_setprio 1
	s_waitcnt lgkmcnt(0)
	v_mfma_f32_16x16x32_bf16 v[94:97], v[130:133], v[206:209], v[94:97]
	v_mfma_f32_16x16x32_bf16 v[90:93], v[150:153], v[206:209], v[90:93]
	v_mfma_f32_16x16x32_bf16 v[86:89], v[130:133], v[214:217], v[86:89]
	v_mfma_f32_16x16x32_bf16 v[82:85], v[150:153], v[214:217], v[82:85]
	s_barrier
	v_mfma_f32_16x16x32_bf16 v[78:81], v[130:133], v[222:225], v[78:81]
	v_mfma_f32_16x16x32_bf16 v[74:77], v[150:153], v[222:225], v[74:77]
	v_mfma_f32_16x16x32_bf16 v[70:73], v[130:133], v[230:233], v[70:73]
	v_mfma_f32_16x16x32_bf16 v[62:65], v[150:153], v[230:233], v[62:65]
	v_mfma_f32_16x16x32_bf16 v[94:97], v[134:137], v[210:213], v[94:97]
	v_mfma_f32_16x16x32_bf16 v[90:93], v[156:159], v[210:213], v[90:93]
	v_mfma_f32_16x16x32_bf16 v[86:89], v[134:137], v[218:221], v[86:89]
	v_mfma_f32_16x16x32_bf16 v[82:85], v[156:159], v[218:221], v[82:85]
	v_mfma_f32_16x16x32_bf16 v[78:81], v[134:137], v[226:229], v[78:81]
	v_mfma_f32_16x16x32_bf16 v[74:77], v[156:159], v[226:229], v[74:77]
	v_mfma_f32_16x16x32_bf16 v[70:73], v[134:137], v[234:237], v[70:73]
	v_mfma_f32_16x16x32_bf16 v[62:65], v[156:159], v[234:237], v[62:65]
	s_setprio 0
	s_setprio 1
	v_mfma_f32_16x16x32_bf16 v[30:33], v[160:163], v[206:209], v[30:33]
	v_mfma_f32_16x16x32_bf16 v[26:29], v[182:185], v[206:209], v[26:29]
	v_mfma_f32_16x16x32_bf16 v[22:25], v[160:163], v[214:217], v[22:25]
	v_mfma_f32_16x16x32_bf16 v[18:21], v[182:185], v[214:217], v[18:21]
	v_mfma_f32_16x16x32_bf16 v[14:17], v[160:163], v[222:225], v[14:17]
	v_mfma_f32_16x16x32_bf16 v[10:13], v[182:185], v[222:225], v[10:13]
	v_mfma_f32_16x16x32_bf16 v[6:9], v[160:163], v[230:233], v[6:9]
	v_mfma_f32_16x16x32_bf16 v[2:5], v[182:185], v[230:233], v[2:5]
	v_mfma_f32_16x16x32_bf16 v[30:33], v[178:181], v[210:213], v[30:33]
	v_mfma_f32_16x16x32_bf16 v[26:29], v[186:189], v[210:213], v[26:29]
	v_mfma_f32_16x16x32_bf16 v[22:25], v[178:181], v[218:221], v[22:25]
	v_mfma_f32_16x16x32_bf16 v[18:21], v[186:189], v[218:221], v[18:21]
	v_mfma_f32_16x16x32_bf16 v[14:17], v[178:181], v[226:229], v[14:17]
	v_mfma_f32_16x16x32_bf16 v[10:13], v[186:189], v[226:229], v[10:13]
	v_mfma_f32_16x16x32_bf16 v[6:9], v[178:181], v[234:237], v[6:9]
	v_mfma_f32_16x16x32_bf16 v[2:5], v[186:189], v[234:237], v[2:5]
	s_barrier
	s_setprio 0
	s_add_i32 s87, s87, 2
	s_add_u32 s68, s68, 0x100
	s_addc_u32 s69, s69, 0
	s_add_u32 s85, s85, 0x100
	s_addc_u32 s86, s86, 0
	s_cmp_gt_u32 s87, 29
	s_cbranch_scc0 .LBB0_795
	s_and_b64 vcc, exec, s[12:13]
	s_cbranch_vccz .LBB0_798
	s_barrier

.LBB0_819:
	s_add_i32 s93, s60, 2
	s_add_u32 s46, s72, 0x80
	s_addc_u32 s47, s73, 0
	s_add_i32 s48, 0, 0x10000
	s_cmp_eq_u32 s87, s60
	s_cselect_b32 s61, s23, s47
	s_cselect_b32 s60, s64, s46
	s_cselect_b32 s47, s21, s92
	s_cselect_b32 s46, s90, s91
	s_add_i32 s49, 0, 0x14000
	v_add_u32_e32 v142, s48, v205
	v_add_u32_e32 v182, s49, v205
	ds_read_b128 v[130:133], v142
	ds_read_b128 v[134:137], v142 offset:1024
	ds_read_b128 v[138:141], v142 offset:2048
	ds_read_b128 v[142:145], v142 offset:3072
	ds_read_b128 v[146:149], v182
	ds_read_b128 v[150:153], v182 offset:1024
	ds_read_b128 v[178:181], v182 offset:2048
	ds_read_b128 v[182:185], v182 offset:3072
	v_lshl_add_u64 v[236:237], s[72:73], 0, v[162:163]
	s_add_i32 m0, s71, 0xc000
	ds_read_b128 v[186:189], v207
	ds_read_b128 v[208:211], v207 offset:1024
	ds_read_b128 v[212:215], v207 offset:2048
	ds_read_b128 v[216:219], v207 offset:3072
	ds_read_b128 v[220:223], v207 offset:4096
	ds_read_b128 v[224:227], v207 offset:5120
	ds_read_b128 v[228:231], v207 offset:6144
	ds_read_b128 v[232:235], v207 offset:7168
	global_load_lds_dwordx4 v[236:237], off
	v_lshl_add_u64 v[236:237], s[72:73], 0, v[164:165]
	s_add_i32 m0, s71, 0xe000
	s_nop 0
	global_load_lds_dwordx4 v[236:237], off
	s_waitcnt vmcnt(8)
	s_waitcnt lgkmcnt(0)
	s_setprio 1
	s_waitcnt lgkmcnt(0)
	v_mfma_f32_16x16x32_bf16 v[126:129], v[130:133], v[186:189], v[126:129]
	v_mfma_f32_16x16x32_bf16 v[122:125], v[138:141], v[186:189], v[122:125]
	v_mfma_f32_16x16x32_bf16 v[118:121], v[130:133], v[212:215], v[118:121]
	v_mfma_f32_16x16x32_bf16 v[114:117], v[138:141], v[212:215], v[114:117]
	s_barrier
	v_mfma_f32_16x16x32_bf16 v[110:113], v[130:133], v[220:223], v[110:113]
	v_mfma_f32_16x16x32_bf16 v[106:109], v[138:141], v[220:223], v[106:109]
	v_mfma_f32_16x16x32_bf16 v[102:105], v[130:133], v[228:231], v[102:105]
	v_mfma_f32_16x16x32_bf16 v[98:101], v[138:141], v[228:231], v[98:101]
	v_mfma_f32_16x16x32_bf16 v[126:129], v[134:137], v[208:211], v[126:129]
	v_mfma_f32_16x16x32_bf16 v[122:125], v[142:145], v[208:211], v[122:125]
	v_mfma_f32_16x16x32_bf16 v[118:121], v[134:137], v[216:219], v[118:121]
	v_mfma_f32_16x16x32_bf16 v[114:117], v[142:145], v[216:219], v[114:117]
	v_mfma_f32_16x16x32_bf16 v[110:113], v[134:137], v[224:227], v[110:113]
	v_mfma_f32_16x16x32_bf16 v[106:109], v[142:145], v[224:227], v[106:109]
	v_mfma_f32_16x16x32_bf16 v[102:105], v[134:137], v[232:235], v[102:105]
	v_mfma_f32_16x16x32_bf16 v[98:101], v[142:145], v[232:235], v[98:101]
	s_setprio 0
	s_setprio 1
	v_mfma_f32_16x16x32_bf16 v[94:97], v[146:149], v[186:189], v[94:97]
	v_mfma_f32_16x16x32_bf16 v[90:93], v[178:181], v[186:189], v[90:93]
	v_mfma_f32_16x16x32_bf16 v[86:89], v[146:149], v[212:215], v[86:89]
	v_mfma_f32_16x16x32_bf16 v[82:85], v[178:181], v[212:215], v[82:85]
	v_mfma_f32_16x16x32_bf16 v[78:81], v[146:149], v[220:223], v[78:81]
	v_mfma_f32_16x16x32_bf16 v[74:77], v[178:181], v[220:223], v[74:77]
	v_mfma_f32_16x16x32_bf16 v[70:73], v[146:149], v[228:231], v[70:73]
	v_mfma_f32_16x16x32_bf16 v[66:69], v[178:181], v[228:231], v[66:69]
	v_mfma_f32_16x16x32_bf16 v[94:97], v[150:153], v[208:211], v[94:97]
	v_mfma_f32_16x16x32_bf16 v[90:93], v[182:185], v[208:211], v[90:93]
	v_mfma_f32_16x16x32_bf16 v[86:89], v[150:153], v[216:219], v[86:89]
	v_mfma_f32_16x16x32_bf16 v[82:85], v[182:185], v[216:219], v[82:85]
	v_mfma_f32_16x16x32_bf16 v[78:81], v[150:153], v[224:227], v[78:81]
	v_mfma_f32_16x16x32_bf16 v[74:77], v[182:185], v[224:227], v[74:77]
	v_mfma_f32_16x16x32_bf16 v[70:73], v[150:153], v[232:235], v[70:73]
	v_mfma_f32_16x16x32_bf16 v[66:69], v[182:185], v[232:235], v[66:69]
	s_barrier
	s_setprio 0
	s_add_i32 s48, s48, s80
	v_lshl_add_u64 v[236:237], s[46:47], 0, v[166:167]
	s_mov_b32 m0, s48
	ds_read_b128 v[186:189], v207 offset:16384
	ds_read_b128 v[208:211], v207 offset:17408
	ds_read_b128 v[212:215], v207 offset:18432
	ds_read_b128 v[216:219], v207 offset:19456
	ds_read_b128 v[220:223], v207 offset:20480
	ds_read_b128 v[224:227], v207 offset:21504
	ds_read_b128 v[228:231], v207 offset:22528
	ds_read_b128 v[232:235], v207 offset:23552
	global_load_lds_dwordx4 v[236:237], off
	s_add_i32 m0, s48, 0x2000
	v_lshl_add_u64 v[242:243], s[46:47], 0, v[158:159]
	s_add_u32 s46, s46, s26
	s_addc_u32 s47, s47, 0
	s_add_i32 s48, s49, s80
	global_load_lds_dwordx4 v[242:243], off
	v_lshl_add_u64 v[244:245], s[46:47], 0, v[166:167]
	s_mov_b32 m0, s48
	v_lshl_add_u64 v[246:247], s[46:47], 0, v[158:159]
	global_load_lds_dwordx4 v[244:245], off
	s_add_i32 m0, s48, 0x2000
	v_lshl_add_u64 v[248:249], s[60:61], 0, v[154:155]
	global_load_lds_dwordx4 v[246:247], off
	s_mov_b32 m0, s71
	v_lshl_add_u64 v[250:251], s[60:61], 0, v[156:157]
	global_load_lds_dwordx4 v[248:249], off
	s_mov_b32 m0, s81
	s_nop 0
	global_load_lds_dwordx4 v[250:251], off
	s_waitcnt vmcnt(8)
	s_waitcnt lgkmcnt(0)
	s_setprio 1
	s_waitcnt lgkmcnt(0)
	v_mfma_f32_16x16x32_bf16 v[62:65], v[130:133], v[186:189], v[62:65]
	v_mfma_f32_16x16x32_bf16 v[58:61], v[138:141], v[186:189], v[58:61]
	v_mfma_f32_16x16x32_bf16 v[54:57], v[130:133], v[212:215], v[54:57]
	v_mfma_f32_16x16x32_bf16 v[50:53], v[138:141], v[212:215], v[50:53]
	s_barrier
	v_mfma_f32_16x16x32_bf16 v[46:49], v[130:133], v[220:223], v[46:49]
	v_mfma_f32_16x16x32_bf16 v[42:45], v[138:141], v[220:223], v[42:45]
	v_mfma_f32_16x16x32_bf16 v[38:41], v[130:133], v[228:231], v[38:41]
	v_mfma_f32_16x16x32_bf16 v[34:37], v[138:141], v[228:231], v[34:37]
	v_mfma_f32_16x16x32_bf16 v[62:65], v[134:137], v[208:211], v[62:65]
	v_mfma_f32_16x16x32_bf16 v[58:61], v[142:145], v[208:211], v[58:61]
	v_mfma_f32_16x16x32_bf16 v[54:57], v[134:137], v[216:219], v[54:57]
	v_mfma_f32_16x16x32_bf16 v[50:53], v[142:145], v[216:219], v[50:53]
	v_mfma_f32_16x16x32_bf16 v[46:49], v[134:137], v[224:227], v[46:49]
	v_mfma_f32_16x16x32_bf16 v[42:45], v[142:145], v[224:227], v[42:45]
	v_mfma_f32_16x16x32_bf16 v[38:41], v[134:137], v[232:235], v[38:41]
	v_mfma_f32_16x16x32_bf16 v[34:37], v[142:145], v[232:235], v[34:37]
	s_setprio 0
	s_setprio 1
	v_mfma_f32_16x16x32_bf16 v[30:33], v[146:149], v[186:189], v[30:33]
	v_mfma_f32_16x16x32_bf16 v[26:29], v[178:181], v[186:189], v[26:29]
	v_mfma_f32_16x16x32_bf16 v[22:25], v[146:149], v[212:215], v[22:25]
	v_mfma_f32_16x16x32_bf16 v[18:21], v[178:181], v[212:215], v[18:21]
	v_mfma_f32_16x16x32_bf16 v[14:17], v[146:149], v[220:223], v[14:17]
	v_mfma_f32_16x16x32_bf16 v[10:13], v[178:181], v[220:223], v[10:13]
	v_mfma_f32_16x16x32_bf16 v[6:9], v[146:149], v[228:231], v[6:9]
	v_mfma_f32_16x16x32_bf16 v[2:5], v[178:181], v[228:231], v[2:5]
	v_mfma_f32_16x16x32_bf16 v[30:33], v[150:153], v[208:211], v[30:33]
	v_mfma_f32_16x16x32_bf16 v[26:29], v[182:185], v[208:211], v[26:29]
	v_mfma_f32_16x16x32_bf16 v[22:25], v[150:153], v[216:219], v[22:25]
	v_mfma_f32_16x16x32_bf16 v[18:21], v[182:185], v[216:219], v[18:21]
	v_mfma_f32_16x16x32_bf16 v[14:17], v[150:153], v[224:227], v[14:17]
	v_mfma_f32_16x16x32_bf16 v[10:13], v[182:185], v[224:227], v[10:13]
	v_mfma_f32_16x16x32_bf16 v[6:9], v[150:153], v[232:235], v[6:9]
	v_mfma_f32_16x16x32_bf16 v[2:5], v[182:185], v[232:235], v[2:5]
	s_barrier
	s_setprio 0
	s_add_i32 s48, 0, 0x18000
	s_add_i32 s49, 0, 0x1c000
	v_add_u32_e32 v142, s48, v205
	v_add_u32_e32 v182, s49, v205
	ds_read_b128 v[130:133], v142
	ds_read_b128 v[134:137], v142 offset:1024
	ds_read_b128 v[138:141], v142 offset:2048
	ds_read_b128 v[142:145], v142 offset:3072
	ds_read_b128 v[146:149], v182
	ds_read_b128 v[150:153], v182 offset:1024
	ds_read_b128 v[178:181], v182 offset:2048
	ds_read_b128 v[182:185], v182 offset:3072
	s_add_u32 s46, s60, s26
	s_addc_u32 s47, s61, 0
	s_mov_b32 m0, s82
	v_lshl_add_u64 v[252:253], s[46:47], 0, v[154:155]
	ds_read_b128 v[186:189], v207 offset:32768
	ds_read_b128 v[208:211], v207 offset:33792
	ds_read_b128 v[212:215], v207 offset:34816
	ds_read_b128 v[216:219], v207 offset:35840
	ds_read_b128 v[220:223], v207 offset:36864
	ds_read_b128 v[224:227], v207 offset:37888
	ds_read_b128 v[228:231], v207 offset:38912
	ds_read_b128 v[232:235], v207 offset:39936
	global_load_lds_dwordx4 v[252:253], off
	v_lshl_add_u64 v[252:253], s[46:47], 0, v[156:157]
	s_mov_b32 m0, s83
	s_nop 0
	global_load_lds_dwordx4 v[252:253], off
	s_waitcnt vmcnt(8)
	s_waitcnt lgkmcnt(0)
	s_setprio 1
	s_waitcnt lgkmcnt(0)
	v_mfma_f32_16x16x32_bf16 v[126:129], v[130:133], v[186:189], v[126:129]
	v_mfma_f32_16x16x32_bf16 v[122:125], v[138:141], v[186:189], v[122:125]
	v_mfma_f32_16x16x32_bf16 v[118:121], v[130:133], v[212:215], v[118:121]
	v_mfma_f32_16x16x32_bf16 v[114:117], v[138:141], v[212:215], v[114:117]
	s_barrier
	v_mfma_f32_16x16x32_bf16 v[110:113], v[130:133], v[220:223], v[110:113]
	v_mfma_f32_16x16x32_bf16 v[106:109], v[138:141], v[220:223], v[106:109]
	v_mfma_f32_16x16x32_bf16 v[102:105], v[130:133], v[228:231], v[102:105]
	v_mfma_f32_16x16x32_bf16 v[98:101], v[138:141], v[228:231], v[98:101]
	v_mfma_f32_16x16x32_bf16 v[126:129], v[134:137], v[208:211], v[126:129]
	v_mfma_f32_16x16x32_bf16 v[122:125], v[142:145], v[208:211], v[122:125]
	v_mfma_f32_16x16x32_bf16 v[118:121], v[134:137], v[216:219], v[118:121]
	v_mfma_f32_16x16x32_bf16 v[114:117], v[142:145], v[216:219], v[114:117]
	v_mfma_f32_16x16x32_bf16 v[110:113], v[134:137], v[224:227], v[110:113]
	v_mfma_f32_16x16x32_bf16 v[106:109], v[142:145], v[224:227], v[106:109]
	v_mfma_f32_16x16x32_bf16 v[102:105], v[134:137], v[232:235], v[102:105]
	v_mfma_f32_16x16x32_bf16 v[98:101], v[142:145], v[232:235], v[98:101]
	s_setprio 0
	s_setprio 1
	v_mfma_f32_16x16x32_bf16 v[94:97], v[146:149], v[186:189], v[94:97]
	v_mfma_f32_16x16x32_bf16 v[90:93], v[178:181], v[186:189], v[90:93]
	v_mfma_f32_16x16x32_bf16 v[86:89], v[146:149], v[212:215], v[86:89]
	v_mfma_f32_16x16x32_bf16 v[82:85], v[178:181], v[212:215], v[82:85]
	v_mfma_f32_16x16x32_bf16 v[78:81], v[146:149], v[220:223], v[78:81]
	v_mfma_f32_16x16x32_bf16 v[74:77], v[178:181], v[220:223], v[74:77]
	v_mfma_f32_16x16x32_bf16 v[70:73], v[146:149], v[228:231], v[70:73]
	v_mfma_f32_16x16x32_bf16 v[66:69], v[178:181], v[228:231], v[66:69]
	v_mfma_f32_16x16x32_bf16 v[94:97], v[150:153], v[208:211], v[94:97]
	v_mfma_f32_16x16x32_bf16 v[90:93], v[182:185], v[208:211], v[90:93]
	v_mfma_f32_16x16x32_bf16 v[86:89], v[150:153], v[216:219], v[86:89]
	v_mfma_f32_16x16x32_bf16 v[82:85], v[182:185], v[216:219], v[82:85]
	v_mfma_f32_16x16x32_bf16 v[78:81], v[150:153], v[224:227], v[78:81]
	v_mfma_f32_16x16x32_bf16 v[74:77], v[182:185], v[224:227], v[74:77]
	v_mfma_f32_16x16x32_bf16 v[70:73], v[150:153], v[232:235], v[70:73]
	v_mfma_f32_16x16x32_bf16 v[66:69], v[182:185], v[232:235], v[66:69]
	s_barrier
	s_setprio 0
	s_add_i32 s46, s48, s80
	v_lshl_add_u64 v[236:237], v[236:237], 0, s[42:43]
	s_mov_b32 m0, s46
	ds_read_b128 v[186:189], v207 offset:49152
	ds_read_b128 v[208:211], v207 offset:50176
	ds_read_b128 v[212:215], v207 offset:51200
	ds_read_b128 v[216:219], v207 offset:52224
	ds_read_b128 v[220:223], v207 offset:53248
	ds_read_b128 v[224:227], v207 offset:54272
	ds_read_b128 v[228:231], v207 offset:55296
	ds_read_b128 v[232:235], v207 offset:56320
	global_load_lds_dwordx4 v[236:237], off
	v_lshl_add_u64 v[236:237], v[242:243], 0, s[42:43]
	s_add_i32 m0, s46, 0x2000
	s_add_i32 s46, s49, s80
	global_load_lds_dwordx4 v[236:237], off
	v_lshl_add_u64 v[236:237], v[244:245], 0, s[42:43]
	s_mov_b32 m0, s46
	s_nop 0
	global_load_lds_dwordx4 v[236:237], off
	v_lshl_add_u64 v[236:237], v[246:247], 0, s[42:43]
	s_add_i32 m0, s46, 0x2000
	s_nop 0
	global_load_lds_dwordx4 v[236:237], off
	v_lshl_add_u64 v[236:237], v[248:249], 0, s[42:43]
	s_mov_b32 m0, s85
	s_nop 0
	global_load_lds_dwordx4 v[236:237], off
	v_lshl_add_u64 v[236:237], v[250:251], 0, s[42:43]
	s_mov_b32 m0, s86
	s_nop 0
	global_load_lds_dwordx4 v[236:237], off
	s_waitcnt vmcnt(8)
	s_waitcnt lgkmcnt(0)
	s_setprio 1
	s_waitcnt lgkmcnt(0)
	v_mfma_f32_16x16x32_bf16 v[62:65], v[130:133], v[186:189], v[62:65]
	v_mfma_f32_16x16x32_bf16 v[58:61], v[138:141], v[186:189], v[58:61]
	v_mfma_f32_16x16x32_bf16 v[54:57], v[130:133], v[212:215], v[54:57]
	v_mfma_f32_16x16x32_bf16 v[50:53], v[138:141], v[212:215], v[50:53]
	s_barrier
	v_mfma_f32_16x16x32_bf16 v[46:49], v[130:133], v[220:223], v[46:49]
	v_mfma_f32_16x16x32_bf16 v[42:45], v[138:141], v[220:223], v[42:45]
	v_mfma_f32_16x16x32_bf16 v[38:41], v[130:133], v[228:231], v[38:41]
	v_mfma_f32_16x16x32_bf16 v[34:37], v[138:141], v[228:231], v[34:37]
	v_mfma_f32_16x16x32_bf16 v[62:65], v[134:137], v[208:211], v[62:65]
	v_mfma_f32_16x16x32_bf16 v[58:61], v[142:145], v[208:211], v[58:61]
	v_mfma_f32_16x16x32_bf16 v[54:57], v[134:137], v[216:219], v[54:57]
	v_mfma_f32_16x16x32_bf16 v[50:53], v[142:145], v[216:219], v[50:53]
	v_mfma_f32_16x16x32_bf16 v[46:49], v[134:137], v[224:227], v[46:49]
	v_mfma_f32_16x16x32_bf16 v[42:45], v[142:145], v[224:227], v[42:45]
	v_mfma_f32_16x16x32_bf16 v[38:41], v[134:137], v[232:235], v[38:41]
	v_mfma_f32_16x16x32_bf16 v[34:37], v[142:145], v[232:235], v[34:37]
	s_setprio 0
	s_setprio 1
	v_mfma_f32_16x16x32_bf16 v[30:33], v[146:149], v[186:189], v[30:33]
	v_mfma_f32_16x16x32_bf16 v[26:29], v[178:181], v[186:189], v[26:29]
	v_mfma_f32_16x16x32_bf16 v[22:25], v[146:149], v[212:215], v[22:25]
	v_mfma_f32_16x16x32_bf16 v[18:21], v[178:181], v[212:215], v[18:21]
	v_mfma_f32_16x16x32_bf16 v[14:17], v[146:149], v[220:223], v[14:17]
	v_mfma_f32_16x16x32_bf16 v[10:13], v[178:181], v[220:223], v[10:13]
	v_mfma_f32_16x16x32_bf16 v[6:9], v[146:149], v[228:231], v[6:9]
	v_mfma_f32_16x16x32_bf16 v[2:5], v[178:181], v[228:231], v[2:5]
	v_mfma_f32_16x16x32_bf16 v[30:33], v[150:153], v[208:211], v[30:33]
	v_mfma_f32_16x16x32_bf16 v[26:29], v[182:185], v[208:211], v[26:29]
	v_mfma_f32_16x16x32_bf16 v[22:25], v[150:153], v[216:219], v[22:25]
	v_mfma_f32_16x16x32_bf16 v[18:21], v[182:185], v[216:219], v[18:21]
	v_mfma_f32_16x16x32_bf16 v[14:17], v[150:153], v[224:227], v[14:17]
	v_mfma_f32_16x16x32_bf16 v[10:13], v[182:185], v[224:227], v[10:13]
	v_mfma_f32_16x16x32_bf16 v[6:9], v[150:153], v[232:235], v[6:9]
	v_mfma_f32_16x16x32_bf16 v[2:5], v[182:185], v[232:235], v[2:5]
	s_barrier
	s_setprio 0
	s_add_u32 s72, s72, 0x100
	s_addc_u32 s73, s73, 0
	s_add_u32 s91, s91, 0x100
	s_addc_u32 s92, s92, 0
	s_cmp_ge_u32 s93, s84
	s_mov_b32 s60, s93
	s_cbranch_scc0 .LBB0_819
	s_and_b64 vcc, exec, s[18:19]
	s_cbranch_vccz .LBB0_822
	s_barrier

.LBB0_903:
	s_add_u32 s46, s66, 0xfff80080
	s_addc_u32 s47, s67, -1
	s_add_i32 s48, 0, 0x10000
	s_cmp_eq_u32 s84, 28
	s_cselect_b32 s69, s17, s47
	s_cselect_b32 s68, s64, s46
	s_cselect_b32 s61, s13, s83
	s_cselect_b32 s60, s81, s82
	s_add_i32 s49, 0, 0x14000
	v_add_u32_e32 v142, s48, v186
	v_add_u32_e32 v164, s49, v186
	ds_read_b128 v[130:133], v142
	ds_read_b128 v[134:137], v142 offset:1024
	ds_read_b128 v[138:141], v142 offset:2048
	ds_read_b128 v[142:145], v142 offset:3072
	ds_read_b128 v[146:149], v164
	ds_read_b128 v[160:163], v164 offset:1024
	ds_read_b128 v[178:181], v164 offset:2048
	ds_read_b128 v[182:185], v164 offset:3072
	v_lshl_add_u64 v[164:165], s[66:67], 0, v[156:157]
	s_add_i32 m0, s74, 0xc000
	ds_read_b128 v[206:209], v188
	ds_read_b128 v[210:213], v188 offset:1024
	ds_read_b128 v[214:217], v188 offset:2048
	ds_read_b128 v[218:221], v188 offset:3072
	ds_read_b128 v[222:225], v188 offset:4096
	ds_read_b128 v[226:229], v188 offset:5120
	ds_read_b128 v[230:233], v188 offset:6144
	ds_read_b128 v[234:237], v188 offset:7168
	global_load_lds_dwordx4 v[164:165], off
	v_lshl_add_u64 v[164:165], s[66:67], 0, v[158:159]
	s_add_i32 m0, s74, 0xe000
	s_nop 0
	global_load_lds_dwordx4 v[164:165], off
	s_waitcnt vmcnt(8)
	s_waitcnt lgkmcnt(0)
	s_setprio 1
	s_waitcnt lgkmcnt(0)
	v_mfma_f32_16x16x32_bf16 v[126:129], v[130:133], v[206:209], v[126:129]
	v_mfma_f32_16x16x32_bf16 v[122:125], v[138:141], v[206:209], v[122:125]
	v_mfma_f32_16x16x32_bf16 v[118:121], v[130:133], v[214:217], v[118:121]
	v_mfma_f32_16x16x32_bf16 v[110:113], v[138:141], v[214:217], v[110:113]
	s_barrier
	v_mfma_f32_16x16x32_bf16 v[94:97], v[130:133], v[222:225], v[94:97]
	v_mfma_f32_16x16x32_bf16 v[90:93], v[138:141], v[222:225], v[90:93]
	v_mfma_f32_16x16x32_bf16 v[82:85], v[130:133], v[230:233], v[82:85]
	v_mfma_f32_16x16x32_bf16 v[74:77], v[138:141], v[230:233], v[74:77]
	v_mfma_f32_16x16x32_bf16 v[126:129], v[134:137], v[210:213], v[126:129]
	v_mfma_f32_16x16x32_bf16 v[122:125], v[142:145], v[210:213], v[122:125]
	v_mfma_f32_16x16x32_bf16 v[118:121], v[134:137], v[218:221], v[118:121]
	v_mfma_f32_16x16x32_bf16 v[110:113], v[142:145], v[218:221], v[110:113]
	v_mfma_f32_16x16x32_bf16 v[94:97], v[134:137], v[226:229], v[94:97]
	v_mfma_f32_16x16x32_bf16 v[90:93], v[142:145], v[226:229], v[90:93]
	v_mfma_f32_16x16x32_bf16 v[82:85], v[134:137], v[234:237], v[82:85]
	v_mfma_f32_16x16x32_bf16 v[74:77], v[142:145], v[234:237], v[74:77]
	s_setprio 0
	s_setprio 1
	v_mfma_f32_16x16x32_bf16 v[114:117], v[146:149], v[206:209], v[114:117]
	v_mfma_f32_16x16x32_bf16 v[106:109], v[178:181], v[206:209], v[106:109]
	v_mfma_f32_16x16x32_bf16 v[102:105], v[146:149], v[214:217], v[102:105]
	v_mfma_f32_16x16x32_bf16 v[98:101], v[178:181], v[214:217], v[98:101]
	v_mfma_f32_16x16x32_bf16 v[86:89], v[146:149], v[222:225], v[86:89]
	v_mfma_f32_16x16x32_bf16 v[78:81], v[178:181], v[222:225], v[78:81]
	v_mfma_f32_16x16x32_bf16 v[70:73], v[146:149], v[230:233], v[70:73]
	v_mfma_f32_16x16x32_bf16 v[66:69], v[178:181], v[230:233], v[66:69]
	v_mfma_f32_16x16x32_bf16 v[114:117], v[160:163], v[210:213], v[114:117]
	v_mfma_f32_16x16x32_bf16 v[106:109], v[182:185], v[210:213], v[106:109]
	v_mfma_f32_16x16x32_bf16 v[102:105], v[160:163], v[218:221], v[102:105]
	v_mfma_f32_16x16x32_bf16 v[98:101], v[182:185], v[218:221], v[98:101]
	v_mfma_f32_16x16x32_bf16 v[86:89], v[160:163], v[226:229], v[86:89]
	v_mfma_f32_16x16x32_bf16 v[78:81], v[182:185], v[226:229], v[78:81]
	v_mfma_f32_16x16x32_bf16 v[70:73], v[160:163], v[234:237], v[70:73]
	v_mfma_f32_16x16x32_bf16 v[66:69], v[182:185], v[234:237], v[66:69]
	s_barrier
	s_setprio 0
	s_add_i32 s46, s48, s73
	v_lshl_add_u64 v[164:165], s[60:61], 0, v[166:167]
	s_mov_b32 m0, s46
	ds_read_b128 v[206:209], v188 offset:16384
	ds_read_b128 v[210:213], v188 offset:17408
	ds_read_b128 v[214:217], v188 offset:18432
	ds_read_b128 v[218:221], v188 offset:19456
	ds_read_b128 v[222:225], v188 offset:20480
	ds_read_b128 v[226:229], v188 offset:21504
	ds_read_b128 v[230:233], v188 offset:22528
	ds_read_b128 v[234:237], v188 offset:23552
	global_load_lds_dwordx4 v[164:165], off
	s_add_i32 m0, s46, 0x2000
	s_add_u32 s46, s60, 0x80000
	v_lshl_add_u64 v[242:243], s[60:61], 0, v[154:155]
	s_addc_u32 s47, s61, 0
	s_add_i32 s48, s49, s73
	global_load_lds_dwordx4 v[242:243], off
	v_lshl_add_u64 v[244:245], s[46:47], 0, v[166:167]
	s_mov_b32 m0, s48
	v_lshl_add_u64 v[246:247], s[68:69], 0, v[152:153]
	global_load_lds_dwordx4 v[244:245], off
	v_lshl_add_u64 v[244:245], s[46:47], 0, v[154:155]
	s_add_i32 m0, s48, 0x2000
	s_nop 0
	global_load_lds_dwordx4 v[244:245], off
	v_lshl_add_u64 v[244:245], s[68:69], 0, v[150:151]
	s_mov_b32 m0, s74
	s_nop 0
	global_load_lds_dwordx4 v[244:245], off
	s_mov_b32 m0, s75
	s_nop 0
	global_load_lds_dwordx4 v[246:247], off
	s_waitcnt vmcnt(8)
	s_waitcnt lgkmcnt(0)
	s_setprio 1
	s_waitcnt lgkmcnt(0)
	v_mfma_f32_16x16x32_bf16 v[62:65], v[130:133], v[206:209], v[62:65]
	v_mfma_f32_16x16x32_bf16 v[58:61], v[138:141], v[206:209], v[58:61]
	v_mfma_f32_16x16x32_bf16 v[50:53], v[130:133], v[214:217], v[50:53]
	v_mfma_f32_16x16x32_bf16 v[42:45], v[138:141], v[214:217], v[42:45]
	s_barrier
	v_mfma_f32_16x16x32_bf16 v[34:37], v[130:133], v[222:225], v[34:37]
	v_mfma_f32_16x16x32_bf16 v[26:29], v[138:141], v[222:225], v[26:29]
	v_mfma_f32_16x16x32_bf16 v[18:21], v[130:133], v[230:233], v[18:21]
	v_mfma_f32_16x16x32_bf16 v[10:13], v[138:141], v[230:233], v[10:13]
	v_mfma_f32_16x16x32_bf16 v[62:65], v[134:137], v[210:213], v[62:65]
	v_mfma_f32_16x16x32_bf16 v[58:61], v[142:145], v[210:213], v[58:61]
	v_mfma_f32_16x16x32_bf16 v[50:53], v[134:137], v[218:221], v[50:53]
	v_mfma_f32_16x16x32_bf16 v[42:45], v[142:145], v[218:221], v[42:45]
	v_mfma_f32_16x16x32_bf16 v[34:37], v[134:137], v[226:229], v[34:37]
	v_mfma_f32_16x16x32_bf16 v[26:29], v[142:145], v[226:229], v[26:29]
	v_mfma_f32_16x16x32_bf16 v[18:21], v[134:137], v[234:237], v[18:21]
	v_mfma_f32_16x16x32_bf16 v[10:13], v[142:145], v[234:237], v[10:13]
	s_setprio 0
	s_setprio 1
	v_mfma_f32_16x16x32_bf16 v[54:57], v[146:149], v[206:209], v[54:57]
	v_mfma_f32_16x16x32_bf16 v[46:49], v[178:181], v[206:209], v[46:49]
	v_mfma_f32_16x16x32_bf16 v[38:41], v[146:149], v[214:217], v[38:41]
	v_mfma_f32_16x16x32_bf16 v[30:33], v[178:181], v[214:217], v[30:33]
	v_mfma_f32_16x16x32_bf16 v[22:25], v[146:149], v[222:225], v[22:25]
	v_mfma_f32_16x16x32_bf16 v[14:17], v[178:181], v[222:225], v[14:17]
	v_mfma_f32_16x16x32_bf16 v[6:9], v[146:149], v[230:233], v[6:9]
	v_mfma_f32_16x16x32_bf16 v[2:5], v[178:181], v[230:233], v[2:5]
	v_mfma_f32_16x16x32_bf16 v[54:57], v[160:163], v[210:213], v[54:57]
	v_mfma_f32_16x16x32_bf16 v[46:49], v[182:185], v[210:213], v[46:49]
	v_mfma_f32_16x16x32_bf16 v[38:41], v[160:163], v[218:221], v[38:41]
	v_mfma_f32_16x16x32_bf16 v[30:33], v[182:185], v[218:221], v[30:33]
	v_mfma_f32_16x16x32_bf16 v[22:25], v[160:163], v[226:229], v[22:25]
	v_mfma_f32_16x16x32_bf16 v[14:17], v[182:185], v[226:229], v[14:17]
	v_mfma_f32_16x16x32_bf16 v[6:9], v[160:163], v[234:237], v[6:9]
	v_mfma_f32_16x16x32_bf16 v[2:5], v[182:185], v[234:237], v[2:5]
	s_barrier
	s_setprio 0
	s_add_i32 s48, 0, 0x18000
	s_add_i32 s49, 0, 0x1c000
	v_add_u32_e32 v142, s48, v186
	v_add_u32_e32 v182, s49, v186
	ds_read_b128 v[130:133], v142
	ds_read_b128 v[134:137], v142 offset:1024
	ds_read_b128 v[138:141], v142 offset:2048
	ds_read_b128 v[142:145], v142 offset:3072
	ds_read_b128 v[146:149], v182
	ds_read_b128 v[160:163], v182 offset:1024
	ds_read_b128 v[178:181], v182 offset:2048
	ds_read_b128 v[182:185], v182 offset:3072
	s_add_u32 s46, s68, 0x80000
	s_addc_u32 s47, s69, 0
	s_mov_b32 m0, s76
	v_lshl_add_u64 v[248:249], s[46:47], 0, v[150:151]
	ds_read_b128 v[206:209], v188 offset:32768
	ds_read_b128 v[210:213], v188 offset:33792
	ds_read_b128 v[214:217], v188 offset:34816
	ds_read_b128 v[218:221], v188 offset:35840
	ds_read_b128 v[222:225], v188 offset:36864
	ds_read_b128 v[226:229], v188 offset:37888
	ds_read_b128 v[230:233], v188 offset:38912
	ds_read_b128 v[234:237], v188 offset:39936
	global_load_lds_dwordx4 v[248:249], off
	v_lshl_add_u64 v[248:249], s[46:47], 0, v[152:153]
	s_mov_b32 m0, s77
	s_nop 0
	global_load_lds_dwordx4 v[248:249], off
	s_waitcnt vmcnt(8)
	s_waitcnt lgkmcnt(0)
	s_setprio 1
	s_waitcnt lgkmcnt(0)
	v_mfma_f32_16x16x32_bf16 v[126:129], v[130:133], v[206:209], v[126:129]
	v_mfma_f32_16x16x32_bf16 v[122:125], v[138:141], v[206:209], v[122:125]
	v_mfma_f32_16x16x32_bf16 v[118:121], v[130:133], v[214:217], v[118:121]
	v_mfma_f32_16x16x32_bf16 v[110:113], v[138:141], v[214:217], v[110:113]
	s_barrier
	v_mfma_f32_16x16x32_bf16 v[94:97], v[130:133], v[222:225], v[94:97]
	v_mfma_f32_16x16x32_bf16 v[90:93], v[138:141], v[222:225], v[90:93]
	v_mfma_f32_16x16x32_bf16 v[82:85], v[130:133], v[230:233], v[82:85]
	v_mfma_f32_16x16x32_bf16 v[74:77], v[138:141], v[230:233], v[74:77]
	v_mfma_f32_16x16x32_bf16 v[126:129], v[134:137], v[210:213], v[126:129]
	v_mfma_f32_16x16x32_bf16 v[122:125], v[142:145], v[210:213], v[122:125]
	v_mfma_f32_16x16x32_bf16 v[118:121], v[134:137], v[218:221], v[118:121]
	v_mfma_f32_16x16x32_bf16 v[110:113], v[142:145], v[218:221], v[110:113]
	v_mfma_f32_16x16x32_bf16 v[94:97], v[134:137], v[226:229], v[94:97]
	v_mfma_f32_16x16x32_bf16 v[90:93], v[142:145], v[226:229], v[90:93]
	v_mfma_f32_16x16x32_bf16 v[82:85], v[134:137], v[234:237], v[82:85]
	v_mfma_f32_16x16x32_bf16 v[74:77], v[142:145], v[234:237], v[74:77]
	s_setprio 0
	s_setprio 1
	v_mfma_f32_16x16x32_bf16 v[114:117], v[146:149], v[206:209], v[114:117]
	v_mfma_f32_16x16x32_bf16 v[106:109], v[178:181], v[206:209], v[106:109]
	v_mfma_f32_16x16x32_bf16 v[102:105], v[146:149], v[214:217], v[102:105]
	v_mfma_f32_16x16x32_bf16 v[98:101], v[178:181], v[214:217], v[98:101]
	v_mfma_f32_16x16x32_bf16 v[86:89], v[146:149], v[222:225], v[86:89]
	v_mfma_f32_16x16x32_bf16 v[78:81], v[178:181], v[222:225], v[78:81]
	v_mfma_f32_16x16x32_bf16 v[70:73], v[146:149], v[230:233], v[70:73]
	v_mfma_f32_16x16x32_bf16 v[66:69], v[178:181], v[230:233], v[66:69]
	v_mfma_f32_16x16x32_bf16 v[114:117], v[160:163], v[210:213], v[114:117]
	v_mfma_f32_16x16x32_bf16 v[106:109], v[182:185], v[210:213], v[106:109]
	v_mfma_f32_16x16x32_bf16 v[102:105], v[160:163], v[218:221], v[102:105]
	v_mfma_f32_16x16x32_bf16 v[98:101], v[182:185], v[218:221], v[98:101]
	v_mfma_f32_16x16x32_bf16 v[86:89], v[160:163], v[226:229], v[86:89]
	v_mfma_f32_16x16x32_bf16 v[78:81], v[182:185], v[226:229], v[78:81]
	v_mfma_f32_16x16x32_bf16 v[70:73], v[160:163], v[234:237], v[70:73]
	v_mfma_f32_16x16x32_bf16 v[66:69], v[182:185], v[234:237], v[66:69]
	s_barrier
	s_setprio 0
	s_add_i32 s46, s48, s73
	v_lshl_add_u64 v[164:165], v[164:165], 0, s[42:43]
	s_mov_b32 m0, s46
	ds_read_b128 v[206:209], v188 offset:49152
	ds_read_b128 v[210:213], v188 offset:50176
	ds_read_b128 v[214:217], v188 offset:51200
	ds_read_b128 v[218:221], v188 offset:52224
	ds_read_b128 v[222:225], v188 offset:53248
	ds_read_b128 v[226:229], v188 offset:54272
	ds_read_b128 v[230:233], v188 offset:55296
	ds_read_b128 v[234:237], v188 offset:56320
	global_load_lds_dwordx4 v[164:165], off
	s_add_i32 m0, s46, 0x2000
	s_add_u32 s46, s60, 0x80080
	v_lshl_add_u64 v[164:165], v[242:243], 0, s[42:43]
	s_addc_u32 s47, s61, 0
	s_add_i32 s48, s49, s73
	global_load_lds_dwordx4 v[164:165], off
	v_lshl_add_u64 v[164:165], s[46:47], 0, v[166:167]
	s_mov_b32 m0, s48
	s_nop 0
	global_load_lds_dwordx4 v[164:165], off
	v_lshl_add_u64 v[164:165], s[46:47], 0, v[154:155]
	s_add_i32 m0, s48, 0x2000
	s_nop 0
	global_load_lds_dwordx4 v[164:165], off
	v_lshl_add_u64 v[164:165], v[244:245], 0, s[42:43]
	s_mov_b32 m0, s78
	s_nop 0
	global_load_lds_dwordx4 v[164:165], off
	v_lshl_add_u64 v[164:165], v[246:247], 0, s[42:43]
	s_mov_b32 m0, s79
	s_nop 0
	global_load_lds_dwordx4 v[164:165], off
	s_waitcnt vmcnt(8)
	s_waitcnt lgkmcnt(0)
	s_setprio 1
	s_waitcnt lgkmcnt(0)
	v_mfma_f32_16x16x32_bf16 v[62:65], v[130:133], v[206:209], v[62:65]
	v_mfma_f32_16x16x32_bf16 v[58:61], v[138:141], v[206:209], v[58:61]
	v_mfma_f32_16x16x32_bf16 v[50:53], v[130:133], v[214:217], v[50:53]
	v_mfma_f32_16x16x32_bf16 v[42:45], v[138:141], v[214:217], v[42:45]
	s_barrier
	v_mfma_f32_16x16x32_bf16 v[34:37], v[130:133], v[222:225], v[34:37]
	v_mfma_f32_16x16x32_bf16 v[26:29], v[138:141], v[222:225], v[26:29]
	v_mfma_f32_16x16x32_bf16 v[18:21], v[130:133], v[230:233], v[18:21]
	v_mfma_f32_16x16x32_bf16 v[10:13], v[138:141], v[230:233], v[10:13]
	v_mfma_f32_16x16x32_bf16 v[62:65], v[134:137], v[210:213], v[62:65]
	v_mfma_f32_16x16x32_bf16 v[58:61], v[142:145], v[210:213], v[58:61]
	v_mfma_f32_16x16x32_bf16 v[50:53], v[134:137], v[218:221], v[50:53]
	v_mfma_f32_16x16x32_bf16 v[42:45], v[142:145], v[218:221], v[42:45]
	v_mfma_f32_16x16x32_bf16 v[34:37], v[134:137], v[226:229], v[34:37]
	v_mfma_f32_16x16x32_bf16 v[26:29], v[142:145], v[226:229], v[26:29]
	v_mfma_f32_16x16x32_bf16 v[18:21], v[134:137], v[234:237], v[18:21]
	v_mfma_f32_16x16x32_bf16 v[10:13], v[142:145], v[234:237], v[10:13]
	s_setprio 0
	s_setprio 1
	v_mfma_f32_16x16x32_bf16 v[54:57], v[146:149], v[206:209], v[54:57]
	v_mfma_f32_16x16x32_bf16 v[46:49], v[178:181], v[206:209], v[46:49]
	v_mfma_f32_16x16x32_bf16 v[38:41], v[146:149], v[214:217], v[38:41]
	v_mfma_f32_16x16x32_bf16 v[30:33], v[178:181], v[214:217], v[30:33]
	v_mfma_f32_16x16x32_bf16 v[22:25], v[146:149], v[222:225], v[22:25]
	v_mfma_f32_16x16x32_bf16 v[14:17], v[178:181], v[222:225], v[14:17]
	v_mfma_f32_16x16x32_bf16 v[6:9], v[146:149], v[230:233], v[6:9]
	v_mfma_f32_16x16x32_bf16 v[2:5], v[178:181], v[230:233], v[2:5]
	v_mfma_f32_16x16x32_bf16 v[54:57], v[160:163], v[210:213], v[54:57]
	v_mfma_f32_16x16x32_bf16 v[46:49], v[182:185], v[210:213], v[46:49]
	v_mfma_f32_16x16x32_bf16 v[38:41], v[160:163], v[218:221], v[38:41]
	v_mfma_f32_16x16x32_bf16 v[30:33], v[182:185], v[218:221], v[30:33]
	v_mfma_f32_16x16x32_bf16 v[22:25], v[160:163], v[226:229], v[22:25]
	v_mfma_f32_16x16x32_bf16 v[14:17], v[182:185], v[226:229], v[14:17]
	v_mfma_f32_16x16x32_bf16 v[6:9], v[160:163], v[234:237], v[6:9]
	v_mfma_f32_16x16x32_bf16 v[2:5], v[182:185], v[234:237], v[2:5]
	s_barrier
	s_setprio 0
	s_add_i32 s84, s84, 2
	s_add_u32 s66, s66, 0x100
	s_addc_u32 s67, s67, 0
	s_add_u32 s82, s82, 0x100
	s_addc_u32 s83, s83, 0
	s_cmp_gt_u32 s84, 29
	s_cbranch_scc0 .LBB0_903
	s_and_b64 vcc, exec, s[10:11]
	s_cbranch_vccz .LBB0_906
	s_barrier

.LBB0_1035:
	s_add_u32 s46, s64, 0xfff80080
	s_addc_u32 s47, s65, -1
	s_add_i32 s48, 0, 0x10000
	s_cmp_eq_u32 s84, 28
	s_cselect_b32 s67, s17, s47
	s_cselect_b32 s66, s80, s46
	v_add_u32_e32 v140, s48, v142
	s_cselect_b32 s61, s13, s83
	s_cselect_b32 s60, s81, s82
	s_add_i32 s49, 0, 0x14000
	ds_read_b128 v[146:149], v140
	ds_read_b128 v[150:153], v140 offset:1024
	ds_read_b128 v[154:157], v140 offset:2048
	ds_read_b128 v[158:161], v140 offset:3072
	v_add_u32_e32 v140, s49, v142
	ds_read_b128 v[162:165], v140
	ds_read_b128 v[178:181], v140 offset:1024
	ds_read_b128 v[182:185], v140 offset:2048
	ds_read_b128 v[186:189], v140 offset:3072
	v_lshl_add_u64 v[140:141], s[64:65], 0, v[136:137]
	s_add_i32 m0, s23, 0xc000
	ds_read_b128 v[206:209], v144
	ds_read_b128 v[210:213], v144 offset:1024
	ds_read_b128 v[214:217], v144 offset:2048
	ds_read_b128 v[218:221], v144 offset:3072
	ds_read_b128 v[222:225], v144 offset:4096
	ds_read_b128 v[226:229], v144 offset:5120
	ds_read_b128 v[230:233], v144 offset:6144
	ds_read_b128 v[234:237], v144 offset:7168
	global_load_lds_dwordx4 v[140:141], off
	v_lshl_add_u64 v[140:141], s[64:65], 0, v[138:139]
	s_add_i32 m0, s23, 0xe000
	s_nop 0
	global_load_lds_dwordx4 v[140:141], off
	s_waitcnt vmcnt(8)
	s_waitcnt lgkmcnt(0)
	s_setprio 1
	s_waitcnt lgkmcnt(0)
	v_mfma_f32_16x16x32_bf16 v[126:129], v[146:149], v[206:209], v[126:129]
	v_mfma_f32_16x16x32_bf16 v[122:125], v[154:157], v[206:209], v[122:125]
	v_mfma_f32_16x16x32_bf16 v[110:113], v[146:149], v[214:217], v[110:113]
	v_mfma_f32_16x16x32_bf16 v[106:109], v[154:157], v[214:217], v[106:109]
	s_barrier
	v_mfma_f32_16x16x32_bf16 v[94:97], v[146:149], v[222:225], v[94:97]
	v_mfma_f32_16x16x32_bf16 v[90:93], v[154:157], v[222:225], v[90:93]
	v_mfma_f32_16x16x32_bf16 v[78:81], v[146:149], v[230:233], v[78:81]
	v_mfma_f32_16x16x32_bf16 v[74:77], v[154:157], v[230:233], v[74:77]
	v_mfma_f32_16x16x32_bf16 v[126:129], v[150:153], v[210:213], v[126:129]
	v_mfma_f32_16x16x32_bf16 v[122:125], v[158:161], v[210:213], v[122:125]
	v_mfma_f32_16x16x32_bf16 v[110:113], v[150:153], v[218:221], v[110:113]
	v_mfma_f32_16x16x32_bf16 v[106:109], v[158:161], v[218:221], v[106:109]
	v_mfma_f32_16x16x32_bf16 v[94:97], v[150:153], v[226:229], v[94:97]
	v_mfma_f32_16x16x32_bf16 v[90:93], v[158:161], v[226:229], v[90:93]
	v_mfma_f32_16x16x32_bf16 v[78:81], v[150:153], v[234:237], v[78:81]
	v_mfma_f32_16x16x32_bf16 v[74:77], v[158:161], v[234:237], v[74:77]
	s_setprio 0
	s_setprio 1
	v_mfma_f32_16x16x32_bf16 v[118:121], v[162:165], v[206:209], v[118:121]
	v_mfma_f32_16x16x32_bf16 v[114:117], v[182:185], v[206:209], v[114:117]
	v_mfma_f32_16x16x32_bf16 v[102:105], v[162:165], v[214:217], v[102:105]
	v_mfma_f32_16x16x32_bf16 v[98:101], v[182:185], v[214:217], v[98:101]
	v_mfma_f32_16x16x32_bf16 v[86:89], v[162:165], v[222:225], v[86:89]
	v_mfma_f32_16x16x32_bf16 v[82:85], v[182:185], v[222:225], v[82:85]
	v_mfma_f32_16x16x32_bf16 v[70:73], v[162:165], v[230:233], v[70:73]
	v_mfma_f32_16x16x32_bf16 v[66:69], v[182:185], v[230:233], v[66:69]
	v_mfma_f32_16x16x32_bf16 v[118:121], v[178:181], v[210:213], v[118:121]
	v_mfma_f32_16x16x32_bf16 v[114:117], v[186:189], v[210:213], v[114:117]
	v_mfma_f32_16x16x32_bf16 v[102:105], v[178:181], v[218:221], v[102:105]
	v_mfma_f32_16x16x32_bf16 v[98:101], v[186:189], v[218:221], v[98:101]
	v_mfma_f32_16x16x32_bf16 v[86:89], v[178:181], v[226:229], v[86:89]
	v_mfma_f32_16x16x32_bf16 v[82:85], v[186:189], v[226:229], v[82:85]
	v_mfma_f32_16x16x32_bf16 v[70:73], v[178:181], v[234:237], v[70:73]
	v_mfma_f32_16x16x32_bf16 v[66:69], v[186:189], v[234:237], v[66:69]
	s_barrier
	s_setprio 0
	s_add_i32 s46, s48, s72
	v_lshl_add_u64 v[140:141], s[60:61], 0, v[166:167]
	s_mov_b32 m0, s46
	ds_read_b128 v[206:209], v144 offset:16384
	ds_read_b128 v[210:213], v144 offset:17408
	ds_read_b128 v[214:217], v144 offset:18432
	ds_read_b128 v[218:221], v144 offset:19456
	ds_read_b128 v[222:225], v144 offset:20480
	ds_read_b128 v[226:229], v144 offset:21504
	ds_read_b128 v[230:233], v144 offset:22528
	ds_read_b128 v[234:237], v144 offset:23552
	global_load_lds_dwordx4 v[140:141], off
	s_add_i32 m0, s46, 0x2000
	s_add_u32 s46, s60, 0x80000
	v_lshl_add_u64 v[242:243], s[60:61], 0, v[134:135]
	s_addc_u32 s47, s61, 0
	s_add_i32 s48, s49, s72
	global_load_lds_dwordx4 v[242:243], off
	v_lshl_add_u64 v[244:245], s[46:47], 0, v[166:167]
	s_mov_b32 m0, s48
	v_lshl_add_u64 v[246:247], s[66:67], 0, v[132:133]
	global_load_lds_dwordx4 v[244:245], off
	v_lshl_add_u64 v[244:245], s[46:47], 0, v[134:135]
	s_add_i32 m0, s48, 0x2000
	s_nop 0
	global_load_lds_dwordx4 v[244:245], off
	v_lshl_add_u64 v[244:245], s[66:67], 0, v[130:131]
	s_mov_b32 m0, s23
	s_nop 0
	global_load_lds_dwordx4 v[244:245], off
	s_mov_b32 m0, s73
	s_nop 0
	global_load_lds_dwordx4 v[246:247], off
	s_waitcnt vmcnt(8)
	s_waitcnt lgkmcnt(0)
	s_setprio 1
	s_waitcnt lgkmcnt(0)
	v_mfma_f32_16x16x32_bf16 v[62:65], v[146:149], v[206:209], v[62:65]
	v_mfma_f32_16x16x32_bf16 v[58:61], v[154:157], v[206:209], v[58:61]
	v_mfma_f32_16x16x32_bf16 v[46:49], v[146:149], v[214:217], v[46:49]
	v_mfma_f32_16x16x32_bf16 v[42:45], v[154:157], v[214:217], v[42:45]
	s_barrier
	v_mfma_f32_16x16x32_bf16 v[30:33], v[146:149], v[222:225], v[30:33]
	v_mfma_f32_16x16x32_bf16 v[26:29], v[154:157], v[222:225], v[26:29]
	v_mfma_f32_16x16x32_bf16 v[14:17], v[146:149], v[230:233], v[14:17]
	v_mfma_f32_16x16x32_bf16 v[10:13], v[154:157], v[230:233], v[10:13]
	v_mfma_f32_16x16x32_bf16 v[62:65], v[150:153], v[210:213], v[62:65]
	v_mfma_f32_16x16x32_bf16 v[58:61], v[158:161], v[210:213], v[58:61]
	v_mfma_f32_16x16x32_bf16 v[46:49], v[150:153], v[218:221], v[46:49]
	v_mfma_f32_16x16x32_bf16 v[42:45], v[158:161], v[218:221], v[42:45]
	v_mfma_f32_16x16x32_bf16 v[30:33], v[150:153], v[226:229], v[30:33]
	v_mfma_f32_16x16x32_bf16 v[26:29], v[158:161], v[226:229], v[26:29]
	v_mfma_f32_16x16x32_bf16 v[14:17], v[150:153], v[234:237], v[14:17]
	v_mfma_f32_16x16x32_bf16 v[10:13], v[158:161], v[234:237], v[10:13]
	s_setprio 0
	s_setprio 1
	v_mfma_f32_16x16x32_bf16 v[54:57], v[162:165], v[206:209], v[54:57]
	v_mfma_f32_16x16x32_bf16 v[50:53], v[182:185], v[206:209], v[50:53]
	v_mfma_f32_16x16x32_bf16 v[38:41], v[162:165], v[214:217], v[38:41]
	v_mfma_f32_16x16x32_bf16 v[34:37], v[182:185], v[214:217], v[34:37]
	v_mfma_f32_16x16x32_bf16 v[22:25], v[162:165], v[222:225], v[22:25]
	v_mfma_f32_16x16x32_bf16 v[18:21], v[182:185], v[222:225], v[18:21]
	v_mfma_f32_16x16x32_bf16 v[6:9], v[162:165], v[230:233], v[6:9]
	v_mfma_f32_16x16x32_bf16 v[2:5], v[182:185], v[230:233], v[2:5]
	v_mfma_f32_16x16x32_bf16 v[54:57], v[178:181], v[210:213], v[54:57]
	v_mfma_f32_16x16x32_bf16 v[50:53], v[186:189], v[210:213], v[50:53]
	v_mfma_f32_16x16x32_bf16 v[38:41], v[178:181], v[218:221], v[38:41]
	v_mfma_f32_16x16x32_bf16 v[34:37], v[186:189], v[218:221], v[34:37]
	v_mfma_f32_16x16x32_bf16 v[22:25], v[178:181], v[226:229], v[22:25]
	v_mfma_f32_16x16x32_bf16 v[18:21], v[186:189], v[226:229], v[18:21]
	v_mfma_f32_16x16x32_bf16 v[6:9], v[178:181], v[234:237], v[6:9]
	v_mfma_f32_16x16x32_bf16 v[2:5], v[186:189], v[234:237], v[2:5]
	s_barrier
	s_setprio 0
	s_add_i32 s48, 0, 0x18000
	v_add_u32_e32 v145, s48, v142
	s_add_i32 s49, 0, 0x1c000
	ds_read_b128 v[146:149], v145
	ds_read_b128 v[150:153], v145 offset:1024
	ds_read_b128 v[154:157], v145 offset:2048
	ds_read_b128 v[158:161], v145 offset:3072
	v_add_u32_e32 v145, s49, v142
	ds_read_b128 v[162:165], v145
	ds_read_b128 v[178:181], v145 offset:1024
	ds_read_b128 v[182:185], v145 offset:2048
	ds_read_b128 v[186:189], v145 offset:3072
	s_add_u32 s46, s66, 0x80000
	s_addc_u32 s47, s67, 0
	s_mov_b32 m0, s74
	v_lshl_add_u64 v[248:249], s[46:47], 0, v[130:131]
	ds_read_b128 v[206:209], v144 offset:32768
	ds_read_b128 v[210:213], v144 offset:33792
	ds_read_b128 v[214:217], v144 offset:34816
	ds_read_b128 v[218:221], v144 offset:35840
	ds_read_b128 v[222:225], v144 offset:36864
	ds_read_b128 v[226:229], v144 offset:37888
	ds_read_b128 v[230:233], v144 offset:38912
	ds_read_b128 v[234:237], v144 offset:39936
	global_load_lds_dwordx4 v[248:249], off
	v_lshl_add_u64 v[248:249], s[46:47], 0, v[132:133]
	s_mov_b32 m0, s75
	s_nop 0
	global_load_lds_dwordx4 v[248:249], off
	s_waitcnt vmcnt(8)
	s_waitcnt lgkmcnt(0)
	s_setprio 1
	s_waitcnt lgkmcnt(0)
	v_mfma_f32_16x16x32_bf16 v[126:129], v[146:149], v[206:209], v[126:129]
	v_mfma_f32_16x16x32_bf16 v[122:125], v[154:157], v[206:209], v[122:125]
	v_mfma_f32_16x16x32_bf16 v[110:113], v[146:149], v[214:217], v[110:113]
	v_mfma_f32_16x16x32_bf16 v[106:109], v[154:157], v[214:217], v[106:109]
	s_barrier
	v_mfma_f32_16x16x32_bf16 v[94:97], v[146:149], v[222:225], v[94:97]
	v_mfma_f32_16x16x32_bf16 v[90:93], v[154:157], v[222:225], v[90:93]
	v_mfma_f32_16x16x32_bf16 v[78:81], v[146:149], v[230:233], v[78:81]
	v_mfma_f32_16x16x32_bf16 v[74:77], v[154:157], v[230:233], v[74:77]
	v_mfma_f32_16x16x32_bf16 v[126:129], v[150:153], v[210:213], v[126:129]
	v_mfma_f32_16x16x32_bf16 v[122:125], v[158:161], v[210:213], v[122:125]
	v_mfma_f32_16x16x32_bf16 v[110:113], v[150:153], v[218:221], v[110:113]
	v_mfma_f32_16x16x32_bf16 v[106:109], v[158:161], v[218:221], v[106:109]
	v_mfma_f32_16x16x32_bf16 v[94:97], v[150:153], v[226:229], v[94:97]
	v_mfma_f32_16x16x32_bf16 v[90:93], v[158:161], v[226:229], v[90:93]
	v_mfma_f32_16x16x32_bf16 v[78:81], v[150:153], v[234:237], v[78:81]
	v_mfma_f32_16x16x32_bf16 v[74:77], v[158:161], v[234:237], v[74:77]
	s_setprio 0
	s_setprio 1
	v_mfma_f32_16x16x32_bf16 v[118:121], v[162:165], v[206:209], v[118:121]
	v_mfma_f32_16x16x32_bf16 v[114:117], v[182:185], v[206:209], v[114:117]
	v_mfma_f32_16x16x32_bf16 v[102:105], v[162:165], v[214:217], v[102:105]
	v_mfma_f32_16x16x32_bf16 v[98:101], v[182:185], v[214:217], v[98:101]
	v_mfma_f32_16x16x32_bf16 v[86:89], v[162:165], v[222:225], v[86:89]
	v_mfma_f32_16x16x32_bf16 v[82:85], v[182:185], v[222:225], v[82:85]
	v_mfma_f32_16x16x32_bf16 v[70:73], v[162:165], v[230:233], v[70:73]
	v_mfma_f32_16x16x32_bf16 v[66:69], v[182:185], v[230:233], v[66:69]
	v_mfma_f32_16x16x32_bf16 v[118:121], v[178:181], v[210:213], v[118:121]
	v_mfma_f32_16x16x32_bf16 v[114:117], v[186:189], v[210:213], v[114:117]
	v_mfma_f32_16x16x32_bf16 v[102:105], v[178:181], v[218:221], v[102:105]
	v_mfma_f32_16x16x32_bf16 v[98:101], v[186:189], v[218:221], v[98:101]
	v_mfma_f32_16x16x32_bf16 v[86:89], v[178:181], v[226:229], v[86:89]
	v_mfma_f32_16x16x32_bf16 v[82:85], v[186:189], v[226:229], v[82:85]
	v_mfma_f32_16x16x32_bf16 v[70:73], v[178:181], v[234:237], v[70:73]
	v_mfma_f32_16x16x32_bf16 v[66:69], v[186:189], v[234:237], v[66:69]
	s_barrier
	s_setprio 0
	s_add_i32 s46, s48, s72
	v_lshl_add_u64 v[140:141], v[140:141], 0, s[42:43]
	s_mov_b32 m0, s46
	ds_read_b128 v[206:209], v144 offset:49152
	ds_read_b128 v[210:213], v144 offset:50176
	ds_read_b128 v[214:217], v144 offset:51200
	ds_read_b128 v[218:221], v144 offset:52224
	ds_read_b128 v[222:225], v144 offset:53248
	ds_read_b128 v[226:229], v144 offset:54272
	ds_read_b128 v[230:233], v144 offset:55296
	ds_read_b128 v[234:237], v144 offset:56320
	global_load_lds_dwordx4 v[140:141], off
	s_add_i32 m0, s46, 0x2000
	s_add_u32 s46, s60, 0x80080
	v_lshl_add_u64 v[140:141], v[242:243], 0, s[42:43]
	s_addc_u32 s47, s61, 0
	s_add_i32 s48, s49, s72
	global_load_lds_dwordx4 v[140:141], off
	v_lshl_add_u64 v[140:141], s[46:47], 0, v[166:167]
	s_mov_b32 m0, s48
	s_nop 0
	global_load_lds_dwordx4 v[140:141], off
	v_lshl_add_u64 v[140:141], s[46:47], 0, v[134:135]
	s_add_i32 m0, s48, 0x2000
	s_nop 0
	global_load_lds_dwordx4 v[140:141], off
	v_lshl_add_u64 v[140:141], v[244:245], 0, s[42:43]
	s_mov_b32 m0, s76
	s_nop 0
	global_load_lds_dwordx4 v[140:141], off
	v_lshl_add_u64 v[140:141], v[246:247], 0, s[42:43]
	s_mov_b32 m0, s77
	s_nop 0
	global_load_lds_dwordx4 v[140:141], off
	s_waitcnt vmcnt(8)
	s_waitcnt lgkmcnt(0)
	s_setprio 1
	s_waitcnt lgkmcnt(0)
	v_mfma_f32_16x16x32_bf16 v[62:65], v[146:149], v[206:209], v[62:65]
	v_mfma_f32_16x16x32_bf16 v[58:61], v[154:157], v[206:209], v[58:61]
	v_mfma_f32_16x16x32_bf16 v[46:49], v[146:149], v[214:217], v[46:49]
	v_mfma_f32_16x16x32_bf16 v[42:45], v[154:157], v[214:217], v[42:45]
	s_barrier
	v_mfma_f32_16x16x32_bf16 v[30:33], v[146:149], v[222:225], v[30:33]
	v_mfma_f32_16x16x32_bf16 v[26:29], v[154:157], v[222:225], v[26:29]
	v_mfma_f32_16x16x32_bf16 v[14:17], v[146:149], v[230:233], v[14:17]
	v_mfma_f32_16x16x32_bf16 v[10:13], v[154:157], v[230:233], v[10:13]
	v_mfma_f32_16x16x32_bf16 v[62:65], v[150:153], v[210:213], v[62:65]
	v_mfma_f32_16x16x32_bf16 v[58:61], v[158:161], v[210:213], v[58:61]
	v_mfma_f32_16x16x32_bf16 v[46:49], v[150:153], v[218:221], v[46:49]
	v_mfma_f32_16x16x32_bf16 v[42:45], v[158:161], v[218:221], v[42:45]
	v_mfma_f32_16x16x32_bf16 v[30:33], v[150:153], v[226:229], v[30:33]
	v_mfma_f32_16x16x32_bf16 v[26:29], v[158:161], v[226:229], v[26:29]
	v_mfma_f32_16x16x32_bf16 v[14:17], v[150:153], v[234:237], v[14:17]
	v_mfma_f32_16x16x32_bf16 v[10:13], v[158:161], v[234:237], v[10:13]
	s_setprio 0
	s_setprio 1
	v_mfma_f32_16x16x32_bf16 v[54:57], v[162:165], v[206:209], v[54:57]
	v_mfma_f32_16x16x32_bf16 v[50:53], v[182:185], v[206:209], v[50:53]
	v_mfma_f32_16x16x32_bf16 v[38:41], v[162:165], v[214:217], v[38:41]
	v_mfma_f32_16x16x32_bf16 v[34:37], v[182:185], v[214:217], v[34:37]
	v_mfma_f32_16x16x32_bf16 v[22:25], v[162:165], v[222:225], v[22:25]
	v_mfma_f32_16x16x32_bf16 v[18:21], v[182:185], v[222:225], v[18:21]
	v_mfma_f32_16x16x32_bf16 v[6:9], v[162:165], v[230:233], v[6:9]
	v_mfma_f32_16x16x32_bf16 v[2:5], v[182:185], v[230:233], v[2:5]
	v_mfma_f32_16x16x32_bf16 v[54:57], v[178:181], v[210:213], v[54:57]
	v_mfma_f32_16x16x32_bf16 v[50:53], v[186:189], v[210:213], v[50:53]
	v_mfma_f32_16x16x32_bf16 v[38:41], v[178:181], v[218:221], v[38:41]
	v_mfma_f32_16x16x32_bf16 v[34:37], v[186:189], v[218:221], v[34:37]
	v_mfma_f32_16x16x32_bf16 v[22:25], v[178:181], v[226:229], v[22:25]
	v_mfma_f32_16x16x32_bf16 v[18:21], v[186:189], v[226:229], v[18:21]
	v_mfma_f32_16x16x32_bf16 v[6:9], v[178:181], v[234:237], v[6:9]
	v_mfma_f32_16x16x32_bf16 v[2:5], v[186:189], v[234:237], v[2:5]
	s_barrier
	s_setprio 0
	s_add_i32 s84, s84, 2
	s_add_u32 s64, s64, 0x100
	s_addc_u32 s65, s65, 0
	s_add_u32 s82, s82, 0x100
	s_addc_u32 s83, s83, 0
	s_cmp_gt_u32 s84, 29
	s_cbranch_scc0 .LBB0_1035
	s_and_b64 vcc, exec, s[10:11]
	s_cbranch_vccz .LBB0_1038
	s_barrier

.LBB0_1112:
	s_add_u32 s46, s64, 0xffe00080
	s_addc_u32 s47, s65, -1
	s_add_i32 s48, 0, 0x10000
	s_cmpk_eq_i32 s84, 0x7c
	s_cselect_b32 s67, s19, s47
	s_cselect_b32 s66, s80, s46
	s_cselect_b32 s61, s17, s83
	s_cselect_b32 s60, s81, s82
	s_add_i32 s49, 0, 0x14000
	v_add_u32_e32 v142, s48, v182
	v_add_u32_e32 v164, s49, v182
	ds_read_b128 v[130:133], v142
	ds_read_b128 v[134:137], v142 offset:1024
	ds_read_b128 v[138:141], v142 offset:2048
	ds_read_b128 v[142:145], v142 offset:3072
	ds_read_b128 v[146:149], v164
	ds_read_b128 v[160:163], v164 offset:1024
	ds_read_b128 v[178:181], v164 offset:2048
	ds_read_b128 v[186:189], v164 offset:3072
	v_lshl_add_u64 v[164:165], s[64:65], 0, v[156:157]
	s_add_i32 m0, s63, 0xc000
	ds_read_b128 v[206:209], v184
	ds_read_b128 v[210:213], v184 offset:1024
	ds_read_b128 v[214:217], v184 offset:2048
	ds_read_b128 v[218:221], v184 offset:3072
	ds_read_b128 v[222:225], v184 offset:4096
	ds_read_b128 v[226:229], v184 offset:5120
	ds_read_b128 v[230:233], v184 offset:6144
	ds_read_b128 v[234:237], v184 offset:7168
	global_load_lds_dwordx4 v[164:165], off
	v_lshl_add_u64 v[164:165], s[64:65], 0, v[158:159]
	s_add_i32 m0, s63, 0xe000
	s_nop 0
	global_load_lds_dwordx4 v[164:165], off
	s_waitcnt vmcnt(8)
	s_waitcnt lgkmcnt(0)
	s_setprio 1
	s_waitcnt lgkmcnt(0)
	v_mfma_f32_16x16x32_bf16 v[126:129], v[130:133], v[206:209], v[126:129]
	v_mfma_f32_16x16x32_bf16 v[122:125], v[138:141], v[206:209], v[122:125]
	v_mfma_f32_16x16x32_bf16 v[118:121], v[130:133], v[214:217], v[118:121]
	v_mfma_f32_16x16x32_bf16 v[114:117], v[138:141], v[214:217], v[114:117]
	s_barrier
	v_mfma_f32_16x16x32_bf16 v[94:97], v[130:133], v[222:225], v[94:97]
	v_mfma_f32_16x16x32_bf16 v[90:93], v[138:141], v[222:225], v[90:93]
	v_mfma_f32_16x16x32_bf16 v[82:85], v[130:133], v[230:233], v[82:85]
	v_mfma_f32_16x16x32_bf16 v[74:77], v[138:141], v[230:233], v[74:77]
	v_mfma_f32_16x16x32_bf16 v[126:129], v[134:137], v[210:213], v[126:129]
	v_mfma_f32_16x16x32_bf16 v[122:125], v[142:145], v[210:213], v[122:125]
	v_mfma_f32_16x16x32_bf16 v[118:121], v[134:137], v[218:221], v[118:121]
	v_mfma_f32_16x16x32_bf16 v[114:117], v[142:145], v[218:221], v[114:117]
	v_mfma_f32_16x16x32_bf16 v[94:97], v[134:137], v[226:229], v[94:97]
	v_mfma_f32_16x16x32_bf16 v[90:93], v[142:145], v[226:229], v[90:93]
	v_mfma_f32_16x16x32_bf16 v[82:85], v[134:137], v[234:237], v[82:85]
	v_mfma_f32_16x16x32_bf16 v[74:77], v[142:145], v[234:237], v[74:77]
	s_setprio 0
	s_setprio 1
	v_mfma_f32_16x16x32_bf16 v[110:113], v[146:149], v[206:209], v[110:113]
	v_mfma_f32_16x16x32_bf16 v[106:109], v[178:181], v[206:209], v[106:109]
	v_mfma_f32_16x16x32_bf16 v[102:105], v[146:149], v[214:217], v[102:105]
	v_mfma_f32_16x16x32_bf16 v[98:101], v[178:181], v[214:217], v[98:101]
	v_mfma_f32_16x16x32_bf16 v[86:89], v[146:149], v[222:225], v[86:89]
	v_mfma_f32_16x16x32_bf16 v[78:81], v[178:181], v[222:225], v[78:81]
	v_mfma_f32_16x16x32_bf16 v[70:73], v[146:149], v[230:233], v[70:73]
	v_mfma_f32_16x16x32_bf16 v[66:69], v[178:181], v[230:233], v[66:69]
	v_mfma_f32_16x16x32_bf16 v[110:113], v[160:163], v[210:213], v[110:113]
	v_mfma_f32_16x16x32_bf16 v[106:109], v[186:189], v[210:213], v[106:109]
	v_mfma_f32_16x16x32_bf16 v[102:105], v[160:163], v[218:221], v[102:105]
	v_mfma_f32_16x16x32_bf16 v[98:101], v[186:189], v[218:221], v[98:101]
	v_mfma_f32_16x16x32_bf16 v[86:89], v[160:163], v[226:229], v[86:89]
	v_mfma_f32_16x16x32_bf16 v[78:81], v[186:189], v[226:229], v[78:81]
	v_mfma_f32_16x16x32_bf16 v[70:73], v[160:163], v[234:237], v[70:73]
	v_mfma_f32_16x16x32_bf16 v[66:69], v[186:189], v[234:237], v[66:69]
	s_barrier
	s_setprio 0
	s_add_i32 s46, s48, s72
	v_lshl_add_u64 v[164:165], s[60:61], 0, v[166:167]
	s_mov_b32 m0, s46
	ds_read_b128 v[206:209], v184 offset:16384
	ds_read_b128 v[210:213], v184 offset:17408
	ds_read_b128 v[214:217], v184 offset:18432
	ds_read_b128 v[218:221], v184 offset:19456
	ds_read_b128 v[222:225], v184 offset:20480
	ds_read_b128 v[226:229], v184 offset:21504
	ds_read_b128 v[230:233], v184 offset:22528
	ds_read_b128 v[234:237], v184 offset:23552
	global_load_lds_dwordx4 v[164:165], off
	s_add_i32 m0, s46, 0x2000
	s_add_u32 s46, s60, 0x200000
	v_lshl_add_u64 v[242:243], s[60:61], 0, v[154:155]
	s_addc_u32 s47, s61, 0
	s_add_i32 s48, s49, s72
	global_load_lds_dwordx4 v[242:243], off
	v_lshl_add_u64 v[244:245], s[46:47], 0, v[166:167]
	s_mov_b32 m0, s48
	v_lshl_add_u64 v[246:247], s[66:67], 0, v[152:153]
	global_load_lds_dwordx4 v[244:245], off
	v_lshl_add_u64 v[244:245], s[46:47], 0, v[154:155]
	s_add_i32 m0, s48, 0x2000
	s_nop 0
	global_load_lds_dwordx4 v[244:245], off
	v_lshl_add_u64 v[244:245], s[66:67], 0, v[150:151]
	s_mov_b32 m0, s63
	s_nop 0
	global_load_lds_dwordx4 v[244:245], off
	s_mov_b32 m0, s73
	s_nop 0
	global_load_lds_dwordx4 v[246:247], off
	s_waitcnt vmcnt(8)
	s_waitcnt lgkmcnt(0)
	s_setprio 1
	s_waitcnt lgkmcnt(0)
	v_mfma_f32_16x16x32_bf16 v[62:65], v[130:133], v[206:209], v[62:65]
	v_mfma_f32_16x16x32_bf16 v[58:61], v[138:141], v[206:209], v[58:61]
	v_mfma_f32_16x16x32_bf16 v[50:53], v[130:133], v[214:217], v[50:53]
	v_mfma_f32_16x16x32_bf16 v[42:45], v[138:141], v[214:217], v[42:45]
	s_barrier
	v_mfma_f32_16x16x32_bf16 v[34:37], v[130:133], v[222:225], v[34:37]
	v_mfma_f32_16x16x32_bf16 v[26:29], v[138:141], v[222:225], v[26:29]
	v_mfma_f32_16x16x32_bf16 v[18:21], v[130:133], v[230:233], v[18:21]
	v_mfma_f32_16x16x32_bf16 v[10:13], v[138:141], v[230:233], v[10:13]
	v_mfma_f32_16x16x32_bf16 v[62:65], v[134:137], v[210:213], v[62:65]
	v_mfma_f32_16x16x32_bf16 v[58:61], v[142:145], v[210:213], v[58:61]
	v_mfma_f32_16x16x32_bf16 v[50:53], v[134:137], v[218:221], v[50:53]
	v_mfma_f32_16x16x32_bf16 v[42:45], v[142:145], v[218:221], v[42:45]
	v_mfma_f32_16x16x32_bf16 v[34:37], v[134:137], v[226:229], v[34:37]
	v_mfma_f32_16x16x32_bf16 v[26:29], v[142:145], v[226:229], v[26:29]
	v_mfma_f32_16x16x32_bf16 v[18:21], v[134:137], v[234:237], v[18:21]
	v_mfma_f32_16x16x32_bf16 v[10:13], v[142:145], v[234:237], v[10:13]
	s_setprio 0
	s_setprio 1
	v_mfma_f32_16x16x32_bf16 v[54:57], v[146:149], v[206:209], v[54:57]
	v_mfma_f32_16x16x32_bf16 v[46:49], v[178:181], v[206:209], v[46:49]
	v_mfma_f32_16x16x32_bf16 v[38:41], v[146:149], v[214:217], v[38:41]
	v_mfma_f32_16x16x32_bf16 v[30:33], v[178:181], v[214:217], v[30:33]
	v_mfma_f32_16x16x32_bf16 v[22:25], v[146:149], v[222:225], v[22:25]
	v_mfma_f32_16x16x32_bf16 v[14:17], v[178:181], v[222:225], v[14:17]
	v_mfma_f32_16x16x32_bf16 v[6:9], v[146:149], v[230:233], v[6:9]
	v_mfma_f32_16x16x32_bf16 v[2:5], v[178:181], v[230:233], v[2:5]
	v_mfma_f32_16x16x32_bf16 v[54:57], v[160:163], v[210:213], v[54:57]
	v_mfma_f32_16x16x32_bf16 v[46:49], v[186:189], v[210:213], v[46:49]
	v_mfma_f32_16x16x32_bf16 v[38:41], v[160:163], v[218:221], v[38:41]
	v_mfma_f32_16x16x32_bf16 v[30:33], v[186:189], v[218:221], v[30:33]
	v_mfma_f32_16x16x32_bf16 v[22:25], v[160:163], v[226:229], v[22:25]
	v_mfma_f32_16x16x32_bf16 v[14:17], v[186:189], v[226:229], v[14:17]
	v_mfma_f32_16x16x32_bf16 v[6:9], v[160:163], v[234:237], v[6:9]
	v_mfma_f32_16x16x32_bf16 v[2:5], v[186:189], v[234:237], v[2:5]
	s_barrier
	s_setprio 0
	s_add_i32 s48, 0, 0x18000
	s_add_i32 s49, 0, 0x1c000
	v_add_u32_e32 v142, s48, v182
	v_add_u32_e32 v185, s49, v182
	ds_read_b128 v[130:133], v142
	ds_read_b128 v[134:137], v142 offset:1024
	ds_read_b128 v[138:141], v142 offset:2048
	ds_read_b128 v[142:145], v142 offset:3072
	ds_read_b128 v[146:149], v185
	ds_read_b128 v[160:163], v185 offset:1024
	ds_read_b128 v[178:181], v185 offset:2048
	ds_read_b128 v[186:189], v185 offset:3072
	s_add_u32 s46, s66, 0x200000
	s_addc_u32 s47, s67, 0
	s_mov_b32 m0, s74
	v_lshl_add_u64 v[248:249], s[46:47], 0, v[150:151]
	ds_read_b128 v[206:209], v184 offset:32768
	ds_read_b128 v[210:213], v184 offset:33792
	ds_read_b128 v[214:217], v184 offset:34816
	ds_read_b128 v[218:221], v184 offset:35840
	ds_read_b128 v[222:225], v184 offset:36864
	ds_read_b128 v[226:229], v184 offset:37888
	ds_read_b128 v[230:233], v184 offset:38912
	ds_read_b128 v[234:237], v184 offset:39936
	global_load_lds_dwordx4 v[248:249], off
	v_lshl_add_u64 v[248:249], s[46:47], 0, v[152:153]
	s_mov_b32 m0, s75
	s_nop 0
	global_load_lds_dwordx4 v[248:249], off
	s_waitcnt vmcnt(8)
	s_waitcnt lgkmcnt(0)
	s_setprio 1
	s_waitcnt lgkmcnt(0)
	v_mfma_f32_16x16x32_bf16 v[126:129], v[130:133], v[206:209], v[126:129]
	v_mfma_f32_16x16x32_bf16 v[122:125], v[138:141], v[206:209], v[122:125]
	v_mfma_f32_16x16x32_bf16 v[118:121], v[130:133], v[214:217], v[118:121]
	v_mfma_f32_16x16x32_bf16 v[114:117], v[138:141], v[214:217], v[114:117]
	s_barrier
	v_mfma_f32_16x16x32_bf16 v[94:97], v[130:133], v[222:225], v[94:97]
	v_mfma_f32_16x16x32_bf16 v[90:93], v[138:141], v[222:225], v[90:93]
	v_mfma_f32_16x16x32_bf16 v[82:85], v[130:133], v[230:233], v[82:85]
	v_mfma_f32_16x16x32_bf16 v[74:77], v[138:141], v[230:233], v[74:77]
	v_mfma_f32_16x16x32_bf16 v[126:129], v[134:137], v[210:213], v[126:129]
	v_mfma_f32_16x16x32_bf16 v[122:125], v[142:145], v[210:213], v[122:125]
	v_mfma_f32_16x16x32_bf16 v[118:121], v[134:137], v[218:221], v[118:121]
	v_mfma_f32_16x16x32_bf16 v[114:117], v[142:145], v[218:221], v[114:117]
	v_mfma_f32_16x16x32_bf16 v[94:97], v[134:137], v[226:229], v[94:97]
	v_mfma_f32_16x16x32_bf16 v[90:93], v[142:145], v[226:229], v[90:93]
	v_mfma_f32_16x16x32_bf16 v[82:85], v[134:137], v[234:237], v[82:85]
	v_mfma_f32_16x16x32_bf16 v[74:77], v[142:145], v[234:237], v[74:77]
	s_setprio 0
	s_setprio 1
	v_mfma_f32_16x16x32_bf16 v[110:113], v[146:149], v[206:209], v[110:113]
	v_mfma_f32_16x16x32_bf16 v[106:109], v[178:181], v[206:209], v[106:109]
	v_mfma_f32_16x16x32_bf16 v[102:105], v[146:149], v[214:217], v[102:105]
	v_mfma_f32_16x16x32_bf16 v[98:101], v[178:181], v[214:217], v[98:101]
	v_mfma_f32_16x16x32_bf16 v[86:89], v[146:149], v[222:225], v[86:89]
	v_mfma_f32_16x16x32_bf16 v[78:81], v[178:181], v[222:225], v[78:81]
	v_mfma_f32_16x16x32_bf16 v[70:73], v[146:149], v[230:233], v[70:73]
	v_mfma_f32_16x16x32_bf16 v[66:69], v[178:181], v[230:233], v[66:69]
	v_mfma_f32_16x16x32_bf16 v[110:113], v[160:163], v[210:213], v[110:113]
	v_mfma_f32_16x16x32_bf16 v[106:109], v[186:189], v[210:213], v[106:109]
	v_mfma_f32_16x16x32_bf16 v[102:105], v[160:163], v[218:221], v[102:105]
	v_mfma_f32_16x16x32_bf16 v[98:101], v[186:189], v[218:221], v[98:101]
	v_mfma_f32_16x16x32_bf16 v[86:89], v[160:163], v[226:229], v[86:89]
	v_mfma_f32_16x16x32_bf16 v[78:81], v[186:189], v[226:229], v[78:81]
	v_mfma_f32_16x16x32_bf16 v[70:73], v[160:163], v[234:237], v[70:73]
	v_mfma_f32_16x16x32_bf16 v[66:69], v[186:189], v[234:237], v[66:69]
	s_barrier
	s_setprio 0
	s_add_i32 s46, s48, s72
	v_lshl_add_u64 v[164:165], v[164:165], 0, s[42:43]
	s_mov_b32 m0, s46
	ds_read_b128 v[206:209], v184 offset:49152
	ds_read_b128 v[210:213], v184 offset:50176
	ds_read_b128 v[214:217], v184 offset:51200
	ds_read_b128 v[218:221], v184 offset:52224
	ds_read_b128 v[222:225], v184 offset:53248
	ds_read_b128 v[226:229], v184 offset:54272
	ds_read_b128 v[230:233], v184 offset:55296
	ds_read_b128 v[234:237], v184 offset:56320
	global_load_lds_dwordx4 v[164:165], off
	s_add_i32 m0, s46, 0x2000
	s_add_u32 s46, s60, 0x200080
	v_lshl_add_u64 v[164:165], v[242:243], 0, s[42:43]
	s_addc_u32 s47, s61, 0
	s_add_i32 s48, s49, s72
	global_load_lds_dwordx4 v[164:165], off
	v_lshl_add_u64 v[164:165], s[46:47], 0, v[166:167]
	s_mov_b32 m0, s48
	s_nop 0
	global_load_lds_dwordx4 v[164:165], off
	v_lshl_add_u64 v[164:165], s[46:47], 0, v[154:155]
	s_add_i32 m0, s48, 0x2000
	s_nop 0
	global_load_lds_dwordx4 v[164:165], off
	v_lshl_add_u64 v[164:165], v[244:245], 0, s[42:43]
	s_mov_b32 m0, s76
	s_nop 0
	global_load_lds_dwordx4 v[164:165], off
	v_lshl_add_u64 v[164:165], v[246:247], 0, s[42:43]
	s_mov_b32 m0, s77
	s_nop 0
	global_load_lds_dwordx4 v[164:165], off
	s_waitcnt vmcnt(8)
	s_waitcnt lgkmcnt(0)
	s_setprio 1
	s_waitcnt lgkmcnt(0)
	v_mfma_f32_16x16x32_bf16 v[62:65], v[130:133], v[206:209], v[62:65]
	v_mfma_f32_16x16x32_bf16 v[58:61], v[138:141], v[206:209], v[58:61]
	v_mfma_f32_16x16x32_bf16 v[50:53], v[130:133], v[214:217], v[50:53]
	v_mfma_f32_16x16x32_bf16 v[42:45], v[138:141], v[214:217], v[42:45]
	s_barrier
	v_mfma_f32_16x16x32_bf16 v[34:37], v[130:133], v[222:225], v[34:37]
	v_mfma_f32_16x16x32_bf16 v[26:29], v[138:141], v[222:225], v[26:29]
	v_mfma_f32_16x16x32_bf16 v[18:21], v[130:133], v[230:233], v[18:21]
	v_mfma_f32_16x16x32_bf16 v[10:13], v[138:141], v[230:233], v[10:13]
	v_mfma_f32_16x16x32_bf16 v[62:65], v[134:137], v[210:213], v[62:65]
	v_mfma_f32_16x16x32_bf16 v[58:61], v[142:145], v[210:213], v[58:61]
	v_mfma_f32_16x16x32_bf16 v[50:53], v[134:137], v[218:221], v[50:53]
	v_mfma_f32_16x16x32_bf16 v[42:45], v[142:145], v[218:221], v[42:45]
	v_mfma_f32_16x16x32_bf16 v[34:37], v[134:137], v[226:229], v[34:37]
	v_mfma_f32_16x16x32_bf16 v[26:29], v[142:145], v[226:229], v[26:29]
	v_mfma_f32_16x16x32_bf16 v[18:21], v[134:137], v[234:237], v[18:21]
	v_mfma_f32_16x16x32_bf16 v[10:13], v[142:145], v[234:237], v[10:13]
	s_setprio 0
	s_setprio 1
	v_mfma_f32_16x16x32_bf16 v[54:57], v[146:149], v[206:209], v[54:57]
	v_mfma_f32_16x16x32_bf16 v[46:49], v[178:181], v[206:209], v[46:49]
	v_mfma_f32_16x16x32_bf16 v[38:41], v[146:149], v[214:217], v[38:41]
	v_mfma_f32_16x16x32_bf16 v[30:33], v[178:181], v[214:217], v[30:33]
	v_mfma_f32_16x16x32_bf16 v[22:25], v[146:149], v[222:225], v[22:25]
	v_mfma_f32_16x16x32_bf16 v[14:17], v[178:181], v[222:225], v[14:17]
	v_mfma_f32_16x16x32_bf16 v[6:9], v[146:149], v[230:233], v[6:9]
	v_mfma_f32_16x16x32_bf16 v[2:5], v[178:181], v[230:233], v[2:5]
	v_mfma_f32_16x16x32_bf16 v[54:57], v[160:163], v[210:213], v[54:57]
	v_mfma_f32_16x16x32_bf16 v[46:49], v[186:189], v[210:213], v[46:49]
	v_mfma_f32_16x16x32_bf16 v[38:41], v[160:163], v[218:221], v[38:41]
	v_mfma_f32_16x16x32_bf16 v[30:33], v[186:189], v[218:221], v[30:33]
	v_mfma_f32_16x16x32_bf16 v[22:25], v[160:163], v[226:229], v[22:25]
	v_mfma_f32_16x16x32_bf16 v[14:17], v[186:189], v[226:229], v[14:17]
	v_mfma_f32_16x16x32_bf16 v[6:9], v[160:163], v[234:237], v[6:9]
	v_mfma_f32_16x16x32_bf16 v[2:5], v[186:189], v[234:237], v[2:5]
	s_barrier
	s_setprio 0
	s_add_i32 s84, s84, 2
	s_add_u32 s64, s64, 0x100
	s_addc_u32 s65, s65, 0
	s_add_u32 s82, s82, 0x100
	s_addc_u32 s83, s83, 0
	s_cmpk_gt_u32 s84, 0x7d
	s_cbranch_scc0 .LBB0_1112
	s_and_b64 vcc, exec, s[12:13]
	s_cbranch_vccz .LBB0_1115
	s_barrier

.LBB0_1138:
	s_add_u32 s46, s62, 0xffe00080
	s_addc_u32 s47, s63, -1
	s_add_i32 s48, 0, 0x10000
	s_cmpk_eq_i32 s82, 0x7c
	s_cselect_b32 s65, s17, s47
	s_cselect_b32 s64, s78, s46
	s_cselect_b32 s61, s13, s81
	s_cselect_b32 s60, s79, s80
	s_add_i32 s49, 0, 0x14000
	v_add_u32_e32 v142, s48, v186
	v_add_u32_e32 v164, s49, v186
	ds_read_b128 v[130:133], v142
	ds_read_b128 v[134:137], v142 offset:1024
	ds_read_b128 v[138:141], v142 offset:2048
	ds_read_b128 v[142:145], v142 offset:3072
	ds_read_b128 v[146:149], v164
	ds_read_b128 v[160:163], v164 offset:1024
	ds_read_b128 v[178:181], v164 offset:2048
	ds_read_b128 v[182:185], v164 offset:3072
	v_lshl_add_u64 v[164:165], s[62:63], 0, v[156:157]
	s_add_i32 m0, s71, 0xc000
	ds_read_b128 v[206:209], v188
	ds_read_b128 v[210:213], v188 offset:1024
	ds_read_b128 v[214:217], v188 offset:2048
	ds_read_b128 v[218:221], v188 offset:3072
	ds_read_b128 v[222:225], v188 offset:4096
	ds_read_b128 v[226:229], v188 offset:5120
	ds_read_b128 v[230:233], v188 offset:6144
	ds_read_b128 v[234:237], v188 offset:7168
	global_load_lds_dwordx4 v[164:165], off
	v_lshl_add_u64 v[164:165], s[62:63], 0, v[158:159]
	s_add_i32 m0, s71, 0xe000
	s_nop 0
	global_load_lds_dwordx4 v[164:165], off
	s_waitcnt vmcnt(8)
	s_waitcnt lgkmcnt(0)
	s_setprio 1
	s_waitcnt lgkmcnt(0)
	v_mfma_f32_16x16x32_bf16 v[126:129], v[130:133], v[206:209], v[126:129]
	v_mfma_f32_16x16x32_bf16 v[122:125], v[138:141], v[206:209], v[122:125]
	v_mfma_f32_16x16x32_bf16 v[118:121], v[130:133], v[214:217], v[118:121]
	v_mfma_f32_16x16x32_bf16 v[110:113], v[138:141], v[214:217], v[110:113]
	s_barrier
	v_mfma_f32_16x16x32_bf16 v[94:97], v[130:133], v[222:225], v[94:97]
	v_mfma_f32_16x16x32_bf16 v[90:93], v[138:141], v[222:225], v[90:93]
	v_mfma_f32_16x16x32_bf16 v[82:85], v[130:133], v[230:233], v[82:85]
	v_mfma_f32_16x16x32_bf16 v[74:77], v[138:141], v[230:233], v[74:77]
	v_mfma_f32_16x16x32_bf16 v[126:129], v[134:137], v[210:213], v[126:129]
	v_mfma_f32_16x16x32_bf16 v[122:125], v[142:145], v[210:213], v[122:125]
	v_mfma_f32_16x16x32_bf16 v[118:121], v[134:137], v[218:221], v[118:121]
	v_mfma_f32_16x16x32_bf16 v[110:113], v[142:145], v[218:221], v[110:113]
	v_mfma_f32_16x16x32_bf16 v[94:97], v[134:137], v[226:229], v[94:97]
	v_mfma_f32_16x16x32_bf16 v[90:93], v[142:145], v[226:229], v[90:93]
	v_mfma_f32_16x16x32_bf16 v[82:85], v[134:137], v[234:237], v[82:85]
	v_mfma_f32_16x16x32_bf16 v[74:77], v[142:145], v[234:237], v[74:77]
	s_setprio 0
	s_setprio 1
	v_mfma_f32_16x16x32_bf16 v[114:117], v[146:149], v[206:209], v[114:117]
	v_mfma_f32_16x16x32_bf16 v[106:109], v[178:181], v[206:209], v[106:109]
	v_mfma_f32_16x16x32_bf16 v[102:105], v[146:149], v[214:217], v[102:105]
	v_mfma_f32_16x16x32_bf16 v[98:101], v[178:181], v[214:217], v[98:101]
	v_mfma_f32_16x16x32_bf16 v[86:89], v[146:149], v[222:225], v[86:89]
	v_mfma_f32_16x16x32_bf16 v[78:81], v[178:181], v[222:225], v[78:81]
	v_mfma_f32_16x16x32_bf16 v[70:73], v[146:149], v[230:233], v[70:73]
	v_mfma_f32_16x16x32_bf16 v[66:69], v[178:181], v[230:233], v[66:69]
	v_mfma_f32_16x16x32_bf16 v[114:117], v[160:163], v[210:213], v[114:117]
	v_mfma_f32_16x16x32_bf16 v[106:109], v[182:185], v[210:213], v[106:109]
	v_mfma_f32_16x16x32_bf16 v[102:105], v[160:163], v[218:221], v[102:105]
	v_mfma_f32_16x16x32_bf16 v[98:101], v[182:185], v[218:221], v[98:101]
	v_mfma_f32_16x16x32_bf16 v[86:89], v[160:163], v[226:229], v[86:89]
	v_mfma_f32_16x16x32_bf16 v[78:81], v[182:185], v[226:229], v[78:81]
	v_mfma_f32_16x16x32_bf16 v[70:73], v[160:163], v[234:237], v[70:73]
	v_mfma_f32_16x16x32_bf16 v[66:69], v[182:185], v[234:237], v[66:69]
	s_barrier
	s_setprio 0
	s_add_i32 s46, s48, s70
	v_lshl_add_u64 v[164:165], s[60:61], 0, v[166:167]
	s_mov_b32 m0, s46
	ds_read_b128 v[206:209], v188 offset:16384
	ds_read_b128 v[210:213], v188 offset:17408
	ds_read_b128 v[214:217], v188 offset:18432
	ds_read_b128 v[218:221], v188 offset:19456
	ds_read_b128 v[222:225], v188 offset:20480
	ds_read_b128 v[226:229], v188 offset:21504
	ds_read_b128 v[230:233], v188 offset:22528
	ds_read_b128 v[234:237], v188 offset:23552
	global_load_lds_dwordx4 v[164:165], off
	s_add_i32 m0, s46, 0x2000
	s_add_u32 s46, s60, 0x200000
	v_lshl_add_u64 v[242:243], s[60:61], 0, v[154:155]
	s_addc_u32 s47, s61, 0
	s_add_i32 s48, s49, s70
	global_load_lds_dwordx4 v[242:243], off
	v_lshl_add_u64 v[244:245], s[46:47], 0, v[166:167]
	s_mov_b32 m0, s48
	v_lshl_add_u64 v[246:247], s[64:65], 0, v[152:153]
	global_load_lds_dwordx4 v[244:245], off
	v_lshl_add_u64 v[244:245], s[46:47], 0, v[154:155]
	s_add_i32 m0, s48, 0x2000
	s_nop 0
	global_load_lds_dwordx4 v[244:245], off
	v_lshl_add_u64 v[244:245], s[64:65], 0, v[150:151]
	s_mov_b32 m0, s71
	s_nop 0
	global_load_lds_dwordx4 v[244:245], off
	s_mov_b32 m0, s72
	s_nop 0
	global_load_lds_dwordx4 v[246:247], off
	s_waitcnt vmcnt(8)
	s_waitcnt lgkmcnt(0)
	s_setprio 1
	s_waitcnt lgkmcnt(0)
	v_mfma_f32_16x16x32_bf16 v[62:65], v[130:133], v[206:209], v[62:65]
	v_mfma_f32_16x16x32_bf16 v[58:61], v[138:141], v[206:209], v[58:61]
	v_mfma_f32_16x16x32_bf16 v[50:53], v[130:133], v[214:217], v[50:53]
	v_mfma_f32_16x16x32_bf16 v[42:45], v[138:141], v[214:217], v[42:45]
	s_barrier
	v_mfma_f32_16x16x32_bf16 v[34:37], v[130:133], v[222:225], v[34:37]
	v_mfma_f32_16x16x32_bf16 v[26:29], v[138:141], v[222:225], v[26:29]
	v_mfma_f32_16x16x32_bf16 v[18:21], v[130:133], v[230:233], v[18:21]
	v_mfma_f32_16x16x32_bf16 v[10:13], v[138:141], v[230:233], v[10:13]
	v_mfma_f32_16x16x32_bf16 v[62:65], v[134:137], v[210:213], v[62:65]
	v_mfma_f32_16x16x32_bf16 v[58:61], v[142:145], v[210:213], v[58:61]
	v_mfma_f32_16x16x32_bf16 v[50:53], v[134:137], v[218:221], v[50:53]
	v_mfma_f32_16x16x32_bf16 v[42:45], v[142:145], v[218:221], v[42:45]
	v_mfma_f32_16x16x32_bf16 v[34:37], v[134:137], v[226:229], v[34:37]
	v_mfma_f32_16x16x32_bf16 v[26:29], v[142:145], v[226:229], v[26:29]
	v_mfma_f32_16x16x32_bf16 v[18:21], v[134:137], v[234:237], v[18:21]
	v_mfma_f32_16x16x32_bf16 v[10:13], v[142:145], v[234:237], v[10:13]
	s_setprio 0
	s_setprio 1
	v_mfma_f32_16x16x32_bf16 v[54:57], v[146:149], v[206:209], v[54:57]
	v_mfma_f32_16x16x32_bf16 v[46:49], v[178:181], v[206:209], v[46:49]
	v_mfma_f32_16x16x32_bf16 v[38:41], v[146:149], v[214:217], v[38:41]
	v_mfma_f32_16x16x32_bf16 v[30:33], v[178:181], v[214:217], v[30:33]
	v_mfma_f32_16x16x32_bf16 v[22:25], v[146:149], v[222:225], v[22:25]
	v_mfma_f32_16x16x32_bf16 v[14:17], v[178:181], v[222:225], v[14:17]
	v_mfma_f32_16x16x32_bf16 v[6:9], v[146:149], v[230:233], v[6:9]
	v_mfma_f32_16x16x32_bf16 v[2:5], v[178:181], v[230:233], v[2:5]
	v_mfma_f32_16x16x32_bf16 v[54:57], v[160:163], v[210:213], v[54:57]
	v_mfma_f32_16x16x32_bf16 v[46:49], v[182:185], v[210:213], v[46:49]
	v_mfma_f32_16x16x32_bf16 v[38:41], v[160:163], v[218:221], v[38:41]
	v_mfma_f32_16x16x32_bf16 v[30:33], v[182:185], v[218:221], v[30:33]
	v_mfma_f32_16x16x32_bf16 v[22:25], v[160:163], v[226:229], v[22:25]
	v_mfma_f32_16x16x32_bf16 v[14:17], v[182:185], v[226:229], v[14:17]
	v_mfma_f32_16x16x32_bf16 v[6:9], v[160:163], v[234:237], v[6:9]
	v_mfma_f32_16x16x32_bf16 v[2:5], v[182:185], v[234:237], v[2:5]
	s_barrier
	s_setprio 0
	s_add_i32 s48, 0, 0x18000
	s_add_i32 s49, 0, 0x1c000
	v_add_u32_e32 v142, s48, v186
	v_add_u32_e32 v182, s49, v186
	ds_read_b128 v[130:133], v142
	ds_read_b128 v[134:137], v142 offset:1024
	ds_read_b128 v[138:141], v142 offset:2048
	ds_read_b128 v[142:145], v142 offset:3072
	ds_read_b128 v[146:149], v182
	ds_read_b128 v[160:163], v182 offset:1024
	ds_read_b128 v[178:181], v182 offset:2048
	ds_read_b128 v[182:185], v182 offset:3072
	s_add_u32 s46, s64, 0x200000
	s_addc_u32 s47, s65, 0
	s_mov_b32 m0, s73
	v_lshl_add_u64 v[248:249], s[46:47], 0, v[150:151]
	ds_read_b128 v[206:209], v188 offset:32768
	ds_read_b128 v[210:213], v188 offset:33792
	ds_read_b128 v[214:217], v188 offset:34816
	ds_read_b128 v[218:221], v188 offset:35840
	ds_read_b128 v[222:225], v188 offset:36864
	ds_read_b128 v[226:229], v188 offset:37888
	ds_read_b128 v[230:233], v188 offset:38912
	ds_read_b128 v[234:237], v188 offset:39936
	global_load_lds_dwordx4 v[248:249], off
	v_lshl_add_u64 v[248:249], s[46:47], 0, v[152:153]
	s_mov_b32 m0, s74
	s_nop 0
	global_load_lds_dwordx4 v[248:249], off
	s_waitcnt vmcnt(8)
	s_waitcnt lgkmcnt(0)
	s_setprio 1
	s_waitcnt lgkmcnt(0)
	v_mfma_f32_16x16x32_bf16 v[126:129], v[130:133], v[206:209], v[126:129]
	v_mfma_f32_16x16x32_bf16 v[122:125], v[138:141], v[206:209], v[122:125]
	v_mfma_f32_16x16x32_bf16 v[118:121], v[130:133], v[214:217], v[118:121]
	v_mfma_f32_16x16x32_bf16 v[110:113], v[138:141], v[214:217], v[110:113]
	s_barrier
	v_mfma_f32_16x16x32_bf16 v[94:97], v[130:133], v[222:225], v[94:97]
	v_mfma_f32_16x16x32_bf16 v[90:93], v[138:141], v[222:225], v[90:93]
	v_mfma_f32_16x16x32_bf16 v[82:85], v[130:133], v[230:233], v[82:85]
	v_mfma_f32_16x16x32_bf16 v[74:77], v[138:141], v[230:233], v[74:77]
	v_mfma_f32_16x16x32_bf16 v[126:129], v[134:137], v[210:213], v[126:129]
	v_mfma_f32_16x16x32_bf16 v[122:125], v[142:145], v[210:213], v[122:125]
	v_mfma_f32_16x16x32_bf16 v[118:121], v[134:137], v[218:221], v[118:121]
	v_mfma_f32_16x16x32_bf16 v[110:113], v[142:145], v[218:221], v[110:113]
	v_mfma_f32_16x16x32_bf16 v[94:97], v[134:137], v[226:229], v[94:97]
	v_mfma_f32_16x16x32_bf16 v[90:93], v[142:145], v[226:229], v[90:93]
	v_mfma_f32_16x16x32_bf16 v[82:85], v[134:137], v[234:237], v[82:85]
	v_mfma_f32_16x16x32_bf16 v[74:77], v[142:145], v[234:237], v[74:77]
	s_setprio 0
	s_setprio 1
	v_mfma_f32_16x16x32_bf16 v[114:117], v[146:149], v[206:209], v[114:117]
	v_mfma_f32_16x16x32_bf16 v[106:109], v[178:181], v[206:209], v[106:109]
	v_mfma_f32_16x16x32_bf16 v[102:105], v[146:149], v[214:217], v[102:105]
	v_mfma_f32_16x16x32_bf16 v[98:101], v[178:181], v[214:217], v[98:101]
	v_mfma_f32_16x16x32_bf16 v[86:89], v[146:149], v[222:225], v[86:89]
	v_mfma_f32_16x16x32_bf16 v[78:81], v[178:181], v[222:225], v[78:81]
	v_mfma_f32_16x16x32_bf16 v[70:73], v[146:149], v[230:233], v[70:73]
	v_mfma_f32_16x16x32_bf16 v[66:69], v[178:181], v[230:233], v[66:69]
	v_mfma_f32_16x16x32_bf16 v[114:117], v[160:163], v[210:213], v[114:117]
	v_mfma_f32_16x16x32_bf16 v[106:109], v[182:185], v[210:213], v[106:109]
	v_mfma_f32_16x16x32_bf16 v[102:105], v[160:163], v[218:221], v[102:105]
	v_mfma_f32_16x16x32_bf16 v[98:101], v[182:185], v[218:221], v[98:101]
	v_mfma_f32_16x16x32_bf16 v[86:89], v[160:163], v[226:229], v[86:89]
	v_mfma_f32_16x16x32_bf16 v[78:81], v[182:185], v[226:229], v[78:81]
	v_mfma_f32_16x16x32_bf16 v[70:73], v[160:163], v[234:237], v[70:73]
	v_mfma_f32_16x16x32_bf16 v[66:69], v[182:185], v[234:237], v[66:69]
	s_barrier
	s_setprio 0
	s_add_i32 s46, s48, s70
	v_lshl_add_u64 v[164:165], v[164:165], 0, s[42:43]
	s_mov_b32 m0, s46
	ds_read_b128 v[206:209], v188 offset:49152
	ds_read_b128 v[210:213], v188 offset:50176
	ds_read_b128 v[214:217], v188 offset:51200
	ds_read_b128 v[218:221], v188 offset:52224
	ds_read_b128 v[222:225], v188 offset:53248
	ds_read_b128 v[226:229], v188 offset:54272
	ds_read_b128 v[230:233], v188 offset:55296
	ds_read_b128 v[234:237], v188 offset:56320
	global_load_lds_dwordx4 v[164:165], off
	s_add_i32 m0, s46, 0x2000
	s_add_u32 s46, s60, 0x200080
	v_lshl_add_u64 v[164:165], v[242:243], 0, s[42:43]
	s_addc_u32 s47, s61, 0
	s_add_i32 s48, s49, s70
	global_load_lds_dwordx4 v[164:165], off
	v_lshl_add_u64 v[164:165], s[46:47], 0, v[166:167]
	s_mov_b32 m0, s48
	s_nop 0
	global_load_lds_dwordx4 v[164:165], off
	v_lshl_add_u64 v[164:165], s[46:47], 0, v[154:155]
	s_add_i32 m0, s48, 0x2000
	s_nop 0
	global_load_lds_dwordx4 v[164:165], off
	v_lshl_add_u64 v[164:165], v[244:245], 0, s[42:43]
	s_mov_b32 m0, s75
	s_nop 0
	global_load_lds_dwordx4 v[164:165], off
	v_lshl_add_u64 v[164:165], v[246:247], 0, s[42:43]
	s_mov_b32 m0, s76
	s_nop 0
	global_load_lds_dwordx4 v[164:165], off
	s_waitcnt vmcnt(8)
	s_waitcnt lgkmcnt(0)
	s_setprio 1
	s_waitcnt lgkmcnt(0)
	v_mfma_f32_16x16x32_bf16 v[62:65], v[130:133], v[206:209], v[62:65]
	v_mfma_f32_16x16x32_bf16 v[58:61], v[138:141], v[206:209], v[58:61]
	v_mfma_f32_16x16x32_bf16 v[50:53], v[130:133], v[214:217], v[50:53]
	v_mfma_f32_16x16x32_bf16 v[42:45], v[138:141], v[214:217], v[42:45]
	s_barrier
	v_mfma_f32_16x16x32_bf16 v[34:37], v[130:133], v[222:225], v[34:37]
	v_mfma_f32_16x16x32_bf16 v[26:29], v[138:141], v[222:225], v[26:29]
	v_mfma_f32_16x16x32_bf16 v[18:21], v[130:133], v[230:233], v[18:21]
	v_mfma_f32_16x16x32_bf16 v[10:13], v[138:141], v[230:233], v[10:13]
	v_mfma_f32_16x16x32_bf16 v[62:65], v[134:137], v[210:213], v[62:65]
	v_mfma_f32_16x16x32_bf16 v[58:61], v[142:145], v[210:213], v[58:61]
	v_mfma_f32_16x16x32_bf16 v[50:53], v[134:137], v[218:221], v[50:53]
	v_mfma_f32_16x16x32_bf16 v[42:45], v[142:145], v[218:221], v[42:45]
	v_mfma_f32_16x16x32_bf16 v[34:37], v[134:137], v[226:229], v[34:37]
	v_mfma_f32_16x16x32_bf16 v[26:29], v[142:145], v[226:229], v[26:29]
	v_mfma_f32_16x16x32_bf16 v[18:21], v[134:137], v[234:237], v[18:21]
	v_mfma_f32_16x16x32_bf16 v[10:13], v[142:145], v[234:237], v[10:13]
	s_setprio 0
	s_setprio 1
	v_mfma_f32_16x16x32_bf16 v[54:57], v[146:149], v[206:209], v[54:57]
	v_mfma_f32_16x16x32_bf16 v[46:49], v[178:181], v[206:209], v[46:49]
	v_mfma_f32_16x16x32_bf16 v[38:41], v[146:149], v[214:217], v[38:41]
	v_mfma_f32_16x16x32_bf16 v[30:33], v[178:181], v[214:217], v[30:33]
	v_mfma_f32_16x16x32_bf16 v[22:25], v[146:149], v[222:225], v[22:25]
	v_mfma_f32_16x16x32_bf16 v[14:17], v[178:181], v[222:225], v[14:17]
	v_mfma_f32_16x16x32_bf16 v[6:9], v[146:149], v[230:233], v[6:9]
	v_mfma_f32_16x16x32_bf16 v[2:5], v[178:181], v[230:233], v[2:5]
	v_mfma_f32_16x16x32_bf16 v[54:57], v[160:163], v[210:213], v[54:57]
	v_mfma_f32_16x16x32_bf16 v[46:49], v[182:185], v[210:213], v[46:49]
	v_mfma_f32_16x16x32_bf16 v[38:41], v[160:163], v[218:221], v[38:41]
	v_mfma_f32_16x16x32_bf16 v[30:33], v[182:185], v[218:221], v[30:33]
	v_mfma_f32_16x16x32_bf16 v[22:25], v[160:163], v[226:229], v[22:25]
	v_mfma_f32_16x16x32_bf16 v[14:17], v[182:185], v[226:229], v[14:17]
	v_mfma_f32_16x16x32_bf16 v[6:9], v[160:163], v[234:237], v[6:9]
	v_mfma_f32_16x16x32_bf16 v[2:5], v[182:185], v[234:237], v[2:5]
	s_barrier
	s_setprio 0
	s_add_i32 s82, s82, 2
	s_add_u32 s62, s62, 0x100
	s_addc_u32 s63, s63, 0
	s_add_u32 s80, s80, 0x100
	s_addc_u32 s81, s81, 0
	s_cmpk_gt_u32 s82, 0x7d
	s_cbranch_scc0 .LBB0_1138
	s_and_b64 vcc, exec, s[10:11]
	s_cbranch_vccz .LBB0_1141
	s_barrier
